# GEMM unit loops: both wave halves run a tile's epilogue in the same barrier interval (leading half waits one barrier at the tile end, trailing half re-staggers before the next tile; phase-end catch-up
# speedup vs baseline: 1.0127x; 1.0023x over previous
.LBB0_226:
	s_ashr_i32 s35, s34, 31
	s_lshl_b64 s[6:7], s[34:35], 20
	v_cmp_lt_i64_e32 vcc, s[38:39], v[156:157]
	s_add_u32 s38, s15, s6
	s_addc_u32 s39, s30, s7
	s_and_b64 s[6:7], vcc, exec
	s_cselect_b32 s5, s39, s21
	s_cselect_b32 s6, s38, s20
	s_ashr_i32 s25, s24, 31
	s_lshl_b64 s[42:43], s[24:25], 20
	s_add_u32 s44, s46, s42
	s_addc_u32 s45, s47, s43
	s_and_b64 s[42:43], vcc, exec
	s_cselect_b32 s7, s45, s23
	s_cselect_b32 s25, s44, s22
	s_add_u32 s20, s20, 0x80080
	s_addc_u32 s21, s21, 0
	s_add_u32 s35, s22, 0x100
	v_mov_b32_e32 v0, 0
	s_addc_u32 s57, s23, 0
	s_mov_b32 s58, -2
	v_mov_b32_e32 v1, v0
	v_mov_b32_e32 v2, v0
	v_mov_b32_e32 v3, v0
	v_mov_b32_e32 v4, v0
	v_mov_b32_e32 v5, v0
	v_mov_b32_e32 v6, v0
	v_mov_b32_e32 v7, v0
	v_mov_b32_e32 v12, v0
	v_mov_b32_e32 v13, v0
	v_mov_b32_e32 v14, v0
	v_mov_b32_e32 v15, v0
	v_mov_b32_e32 v20, v0
	v_mov_b32_e32 v21, v0
	v_mov_b32_e32 v22, v0
	v_mov_b32_e32 v23, v0
	v_mov_b32_e32 v28, v0
	v_mov_b32_e32 v29, v0
	v_mov_b32_e32 v30, v0
	v_mov_b32_e32 v31, v0
	v_mov_b32_e32 v36, v0
	v_mov_b32_e32 v37, v0
	v_mov_b32_e32 v38, v0
	v_mov_b32_e32 v39, v0
	v_mov_b32_e32 v44, v0
	v_mov_b32_e32 v45, v0
	v_mov_b32_e32 v46, v0
	v_mov_b32_e32 v47, v0
	v_mov_b32_e32 v52, v0
	v_mov_b32_e32 v53, v0
	v_mov_b32_e32 v54, v0
	v_mov_b32_e32 v55, v0
	v_mov_b32_e32 v8, v0
	v_mov_b32_e32 v9, v0
	v_mov_b32_e32 v10, v0
	v_mov_b32_e32 v11, v0
	v_mov_b32_e32 v16, v0
	v_mov_b32_e32 v17, v0
	v_mov_b32_e32 v18, v0
	v_mov_b32_e32 v19, v0
	v_mov_b32_e32 v24, v0
	v_mov_b32_e32 v25, v0
	v_mov_b32_e32 v26, v0
	v_mov_b32_e32 v27, v0
	v_mov_b32_e32 v32, v0
	v_mov_b32_e32 v33, v0
	v_mov_b32_e32 v34, v0
	v_mov_b32_e32 v35, v0
	v_mov_b32_e32 v40, v0
	v_mov_b32_e32 v41, v0
	v_mov_b32_e32 v42, v0
	v_mov_b32_e32 v43, v0
	v_mov_b32_e32 v48, v0
	v_mov_b32_e32 v49, v0
	v_mov_b32_e32 v50, v0
	v_mov_b32_e32 v51, v0
	v_mov_b32_e32 v56, v0
	v_mov_b32_e32 v57, v0
	v_mov_b32_e32 v58, v0
	v_mov_b32_e32 v59, v0
	v_mov_b32_e32 v60, v0
	v_mov_b32_e32 v61, v0
	v_mov_b32_e32 v62, v0
	v_mov_b32_e32 v63, v0
	v_mov_b32_e32 v64, v0
	v_mov_b32_e32 v65, v0
	v_mov_b32_e32 v66, v0
	v_mov_b32_e32 v67, v0
	v_mov_b32_e32 v68, v0
	v_mov_b32_e32 v69, v0
	v_mov_b32_e32 v70, v0
	v_mov_b32_e32 v71, v0
	v_mov_b32_e32 v80, v0
	v_mov_b32_e32 v81, v0
	v_mov_b32_e32 v82, v0
	v_mov_b32_e32 v83, v0
	v_mov_b32_e32 v84, v0
	v_mov_b32_e32 v85, v0
	v_mov_b32_e32 v86, v0
	v_mov_b32_e32 v87, v0
	v_mov_b32_e32 v96, v0
	v_mov_b32_e32 v97, v0
	v_mov_b32_e32 v98, v0
	v_mov_b32_e32 v99, v0
	v_mov_b32_e32 v100, v0
	v_mov_b32_e32 v101, v0
	v_mov_b32_e32 v102, v0
	v_mov_b32_e32 v103, v0
	v_mov_b32_e32 v112, v0
	v_mov_b32_e32 v113, v0
	v_mov_b32_e32 v114, v0
	v_mov_b32_e32 v115, v0
	v_mov_b32_e32 v116, v0
	v_mov_b32_e32 v117, v0
	v_mov_b32_e32 v118, v0
	v_mov_b32_e32 v119, v0
	v_mov_b32_e32 v72, v0
	v_mov_b32_e32 v73, v0
	v_mov_b32_e32 v74, v0
	v_mov_b32_e32 v75, v0
	v_mov_b32_e32 v76, v0
	v_mov_b32_e32 v77, v0
	v_mov_b32_e32 v78, v0
	v_mov_b32_e32 v79, v0
	v_mov_b32_e32 v88, v0
	v_mov_b32_e32 v89, v0
	v_mov_b32_e32 v90, v0
	v_mov_b32_e32 v91, v0
	v_mov_b32_e32 v92, v0
	v_mov_b32_e32 v93, v0
	v_mov_b32_e32 v94, v0
	v_mov_b32_e32 v95, v0
	v_mov_b32_e32 v104, v0
	v_mov_b32_e32 v105, v0
	v_mov_b32_e32 v106, v0
	v_mov_b32_e32 v107, v0
	v_mov_b32_e32 v108, v0
	v_mov_b32_e32 v109, v0
	v_mov_b32_e32 v110, v0
	v_mov_b32_e32 v111, v0
	v_mov_b32_e32 v120, v0
	v_mov_b32_e32 v121, v0
	v_mov_b32_e32 v122, v0
	v_mov_b32_e32 v123, v0
	v_mov_b32_e32 v124, v0
	v_mov_b32_e32 v125, v0
	v_mov_b32_e32 v126, v0
	v_mov_b32_e32 v127, v0
	s_cmpk_lt_u32 s14, 0x100
	s_cbranch_scc1 .Lal_e1_p
	s_cmp_lt_u32 s55, 2
	s_cbranch_scc1 .Lal_e1_p
	s_barrier
.Lal_e1_p:
	v_add_u32_e32 v234, 0x10000, v165
	v_add_u32_e32 v235, 0x14000, v165
	v_add_u32_e32 v236, 0x18000, v165
	v_add_u32_e32 v237, 0x1c000, v165
	s_add_u32 s22, s20, 0xfff80080
	s_addc_u32 s23, s21, -1
	s_add_i32 s59, 0, 0x10000
	s_cmp_eq_u32 s58, 28
	s_cselect_b32 s43, s5, s23
	s_cselect_b32 s42, s6, s22
	s_cselect_b32 s23, s7, s57
	s_cselect_b32 s22, s25, s35
	s_add_i32 m0, s49, 0xc000
.LBB0_227:
	ds_read_b128 v[140:143], v234
	ds_read_b128 v[144:147], v234 offset:1024
	ds_read_b128 v[148:151], v234 offset:2048
	ds_read_b128 v[170:173], v234 offset:3072
	ds_read_b128 v[174:177], v168
	ds_read_b128 v[178:181], v168 offset:1024
	ds_read_b128 v[182:185], v168 offset:2048
	ds_read_b128 v[186:189], v168 offset:3072
	ds_read_b128 v[190:193], v168 offset:4096
	ds_read_b128 v[206:209], v168 offset:5120
	ds_read_b128 v[210:213], v168 offset:6144
	ds_read_b128 v[214:217], v168 offset:7168
	global_load_lds_dwordx4 v136, s[20:21]
	s_add_i32 m0, s49, 0xe000
	s_nop 0
	global_load_lds_dwordx4 v138, s[20:21]
	s_waitcnt lgkmcnt(8)
	s_barrier
	s_waitcnt lgkmcnt(0)
	v_mfma_f32_16x16x32_bf16 v[124:127], v[140:143], v[174:177], v[124:127]
	v_mfma_f32_16x16x32_bf16 v[120:123], v[148:151], v[174:177], v[120:123]
	v_mfma_f32_16x16x32_bf16 v[108:111], v[140:143], v[182:185], v[108:111]
	v_mfma_f32_16x16x32_bf16 v[104:107], v[148:151], v[182:185], v[104:107]
	v_mfma_f32_16x16x32_bf16 v[92:95], v[140:143], v[190:193], v[92:95]
	v_mfma_f32_16x16x32_bf16 v[88:91], v[148:151], v[190:193], v[88:91]
	v_mfma_f32_16x16x32_bf16 v[76:79], v[140:143], v[210:213], v[76:79]
	v_mfma_f32_16x16x32_bf16 v[72:75], v[148:151], v[210:213], v[72:75]
	v_mfma_f32_16x16x32_bf16 v[124:127], v[144:147], v[178:181], v[124:127]
	v_mfma_f32_16x16x32_bf16 v[120:123], v[170:173], v[178:181], v[120:123]
	v_mfma_f32_16x16x32_bf16 v[108:111], v[144:147], v[186:189], v[108:111]
	v_mfma_f32_16x16x32_bf16 v[104:107], v[170:173], v[186:189], v[104:107]
	v_mfma_f32_16x16x32_bf16 v[92:95], v[144:147], v[206:209], v[92:95]
	v_mfma_f32_16x16x32_bf16 v[88:91], v[170:173], v[206:209], v[88:91]
	v_mfma_f32_16x16x32_bf16 v[76:79], v[144:147], v[214:217], v[76:79]
	v_mfma_f32_16x16x32_bf16 v[72:75], v[170:173], v[214:217], v[72:75]
	s_barrier
	s_add_i32 s62, 0, 0x14000
	s_add_i32 s59, s59, s48
	s_mov_b32 m0, s59
	ds_read_b128 v[218:221], v235
	ds_read_b128 v[222:225], v235 offset:1024
	ds_read_b128 v[226:229], v235 offset:2048
	ds_read_b128 v[230:233], v235 offset:3072
	global_load_lds_dwordx4 v130, s[22:23]
	s_add_i32 m0, s59, 0x2000
	s_nop 0
	global_load_lds_dwordx4 v134, s[22:23]
	s_barrier
	s_waitcnt lgkmcnt(0)
	v_mfma_f32_16x16x32_bf16 v[116:119], v[218:221], v[174:177], v[116:119]
	v_mfma_f32_16x16x32_bf16 v[112:115], v[226:229], v[174:177], v[112:115]
	v_mfma_f32_16x16x32_bf16 v[100:103], v[218:221], v[182:185], v[100:103]
	v_mfma_f32_16x16x32_bf16 v[96:99], v[226:229], v[182:185], v[96:99]
	v_mfma_f32_16x16x32_bf16 v[84:87], v[218:221], v[190:193], v[84:87]
	v_mfma_f32_16x16x32_bf16 v[80:83], v[226:229], v[190:193], v[80:83]
	v_mfma_f32_16x16x32_bf16 v[68:71], v[218:221], v[210:213], v[68:71]
	v_mfma_f32_16x16x32_bf16 v[64:67], v[226:229], v[210:213], v[64:67]
	v_mfma_f32_16x16x32_bf16 v[116:119], v[222:225], v[178:181], v[116:119]
	v_mfma_f32_16x16x32_bf16 v[112:115], v[230:233], v[178:181], v[112:115]
	v_mfma_f32_16x16x32_bf16 v[100:103], v[222:225], v[186:189], v[100:103]
	v_mfma_f32_16x16x32_bf16 v[96:99], v[230:233], v[186:189], v[96:99]
	v_mfma_f32_16x16x32_bf16 v[84:87], v[222:225], v[206:209], v[84:87]
	v_mfma_f32_16x16x32_bf16 v[80:83], v[230:233], v[206:209], v[80:83]
	v_mfma_f32_16x16x32_bf16 v[68:71], v[222:225], v[214:217], v[68:71]
	v_mfma_f32_16x16x32_bf16 v[64:67], v[230:233], v[214:217], v[64:67]
	s_barrier
	s_mov_b32 m0, s49
	s_add_u32 s98, s42, 0x80
	s_addc_u32 s99, s43, 0
	ds_read_b128 v[174:177], v168 offset:16384
	ds_read_b128 v[178:181], v168 offset:17408
	ds_read_b128 v[182:185], v168 offset:18432
	ds_read_b128 v[186:189], v168 offset:19456
	ds_read_b128 v[190:193], v168 offset:20480
	ds_read_b128 v[206:209], v168 offset:21504
	ds_read_b128 v[210:213], v168 offset:22528
	ds_read_b128 v[214:217], v168 offset:23552
	global_load_lds_dwordx4 v128, s[42:43]
	s_mov_b32 m0, s50
	s_nop 0
	global_load_lds_dwordx4 v132, s[42:43]
	s_barrier
	s_waitcnt lgkmcnt(0)
	v_mfma_f32_16x16x32_bf16 v[60:63], v[140:143], v[174:177], v[60:63]
	v_mfma_f32_16x16x32_bf16 v[56:59], v[148:151], v[174:177], v[56:59]
	v_mfma_f32_16x16x32_bf16 v[48:51], v[140:143], v[182:185], v[48:51]
	v_mfma_f32_16x16x32_bf16 v[40:43], v[148:151], v[182:185], v[40:43]
	v_mfma_f32_16x16x32_bf16 v[32:35], v[140:143], v[190:193], v[32:35]
	v_mfma_f32_16x16x32_bf16 v[24:27], v[148:151], v[190:193], v[24:27]
	v_mfma_f32_16x16x32_bf16 v[16:19], v[140:143], v[210:213], v[16:19]
	v_mfma_f32_16x16x32_bf16 v[8:11], v[148:151], v[210:213], v[8:11]
	v_mfma_f32_16x16x32_bf16 v[60:63], v[144:147], v[178:181], v[60:63]
	v_mfma_f32_16x16x32_bf16 v[56:59], v[170:173], v[178:181], v[56:59]
	v_mfma_f32_16x16x32_bf16 v[48:51], v[144:147], v[186:189], v[48:51]
	v_mfma_f32_16x16x32_bf16 v[40:43], v[170:173], v[186:189], v[40:43]
	v_mfma_f32_16x16x32_bf16 v[32:35], v[144:147], v[206:209], v[32:35]
	v_mfma_f32_16x16x32_bf16 v[24:27], v[170:173], v[206:209], v[24:27]
	v_mfma_f32_16x16x32_bf16 v[16:19], v[144:147], v[214:217], v[16:19]
	v_mfma_f32_16x16x32_bf16 v[8:11], v[170:173], v[214:217], v[8:11]
	s_barrier
	s_add_u32 s60, s22, 0x80000
	s_addc_u32 s61, s23, 0
	s_add_i32 s59, s62, s48
	s_mov_b32 m0, s59
	s_nop 0
	global_load_lds_dwordx4 v130, s[60:61]
	s_add_i32 m0, s59, 0x2000
	s_nop 0
	global_load_lds_dwordx4 v134, s[60:61]
	s_add_i32 s59, 0, 0x18000
	s_add_u32 s42, s42, 0x80000
	s_addc_u32 s43, s43, 0
	s_mov_b32 m0, s51
	s_waitcnt vmcnt(6)
	s_barrier
	v_mfma_f32_16x16x32_bf16 v[52:55], v[218:221], v[174:177], v[52:55]
	v_mfma_f32_16x16x32_bf16 v[44:47], v[226:229], v[174:177], v[44:47]
	v_mfma_f32_16x16x32_bf16 v[36:39], v[218:221], v[182:185], v[36:39]
	v_mfma_f32_16x16x32_bf16 v[28:31], v[226:229], v[182:185], v[28:31]
	v_mfma_f32_16x16x32_bf16 v[20:23], v[218:221], v[190:193], v[20:23]
	v_mfma_f32_16x16x32_bf16 v[12:15], v[226:229], v[190:193], v[12:15]
	v_mfma_f32_16x16x32_bf16 v[4:7], v[218:221], v[210:213], v[4:7]
	v_mfma_f32_16x16x32_bf16 v[0:3], v[226:229], v[210:213], v[0:3]
	v_mfma_f32_16x16x32_bf16 v[52:55], v[222:225], v[178:181], v[52:55]
	v_mfma_f32_16x16x32_bf16 v[44:47], v[230:233], v[178:181], v[44:47]
	v_mfma_f32_16x16x32_bf16 v[36:39], v[222:225], v[186:189], v[36:39]
	v_mfma_f32_16x16x32_bf16 v[28:31], v[230:233], v[186:189], v[28:31]
	v_mfma_f32_16x16x32_bf16 v[20:23], v[222:225], v[206:209], v[20:23]
	v_mfma_f32_16x16x32_bf16 v[12:15], v[230:233], v[206:209], v[12:15]
	v_mfma_f32_16x16x32_bf16 v[4:7], v[222:225], v[214:217], v[4:7]
	v_mfma_f32_16x16x32_bf16 v[0:3], v[230:233], v[214:217], v[0:3]
	s_barrier
	ds_read_b128 v[140:143], v236
	ds_read_b128 v[144:147], v236 offset:1024
	ds_read_b128 v[148:151], v236 offset:2048
	ds_read_b128 v[170:173], v236 offset:3072
	ds_read_b128 v[174:177], v168 offset:32768
	ds_read_b128 v[178:181], v168 offset:33792
	ds_read_b128 v[182:185], v168 offset:34816
	ds_read_b128 v[186:189], v168 offset:35840
	ds_read_b128 v[190:193], v168 offset:36864
	ds_read_b128 v[206:209], v168 offset:37888
	ds_read_b128 v[210:213], v168 offset:38912
	ds_read_b128 v[214:217], v168 offset:39936
	global_load_lds_dwordx4 v128, s[42:43]
	s_mov_b32 m0, s52
	s_nop 0
	global_load_lds_dwordx4 v132, s[42:43]
	s_waitcnt lgkmcnt(8)
	s_barrier
	s_waitcnt lgkmcnt(0)
	v_mfma_f32_16x16x32_bf16 v[124:127], v[140:143], v[174:177], v[124:127]
	v_mfma_f32_16x16x32_bf16 v[120:123], v[148:151], v[174:177], v[120:123]
	v_mfma_f32_16x16x32_bf16 v[108:111], v[140:143], v[182:185], v[108:111]
	v_mfma_f32_16x16x32_bf16 v[104:107], v[148:151], v[182:185], v[104:107]
	v_mfma_f32_16x16x32_bf16 v[92:95], v[140:143], v[190:193], v[92:95]
	v_mfma_f32_16x16x32_bf16 v[88:91], v[148:151], v[190:193], v[88:91]
	v_mfma_f32_16x16x32_bf16 v[76:79], v[140:143], v[210:213], v[76:79]
	v_mfma_f32_16x16x32_bf16 v[72:75], v[148:151], v[210:213], v[72:75]
	v_mfma_f32_16x16x32_bf16 v[124:127], v[144:147], v[178:181], v[124:127]
	v_mfma_f32_16x16x32_bf16 v[120:123], v[170:173], v[178:181], v[120:123]
	v_mfma_f32_16x16x32_bf16 v[108:111], v[144:147], v[186:189], v[108:111]
	v_mfma_f32_16x16x32_bf16 v[104:107], v[170:173], v[186:189], v[104:107]
	v_mfma_f32_16x16x32_bf16 v[92:95], v[144:147], v[206:209], v[92:95]
	v_mfma_f32_16x16x32_bf16 v[88:91], v[170:173], v[206:209], v[88:91]
	v_mfma_f32_16x16x32_bf16 v[76:79], v[144:147], v[214:217], v[76:79]
	v_mfma_f32_16x16x32_bf16 v[72:75], v[170:173], v[214:217], v[72:75]
	s_barrier
	s_add_i32 s42, 0, 0x1c000
	s_add_i32 s43, s59, s48
	s_add_u32 s100, s22, 0x80
	s_addc_u32 s101, s23, 0
	s_mov_b32 m0, s43
	ds_read_b128 v[218:221], v237
	ds_read_b128 v[222:225], v237 offset:1024
	ds_read_b128 v[226:229], v237 offset:2048
	ds_read_b128 v[230:233], v237 offset:3072
	global_load_lds_dwordx4 v130, s[100:101]
	s_add_i32 m0, s43, 0x2000
	s_nop 0
	global_load_lds_dwordx4 v134, s[100:101]
	s_barrier
	s_waitcnt lgkmcnt(0)
	v_mfma_f32_16x16x32_bf16 v[116:119], v[218:221], v[174:177], v[116:119]
	v_mfma_f32_16x16x32_bf16 v[112:115], v[226:229], v[174:177], v[112:115]
	v_mfma_f32_16x16x32_bf16 v[100:103], v[218:221], v[182:185], v[100:103]
	v_mfma_f32_16x16x32_bf16 v[96:99], v[226:229], v[182:185], v[96:99]
	v_mfma_f32_16x16x32_bf16 v[84:87], v[218:221], v[190:193], v[84:87]
	v_mfma_f32_16x16x32_bf16 v[80:83], v[226:229], v[190:193], v[80:83]
	v_mfma_f32_16x16x32_bf16 v[68:71], v[218:221], v[210:213], v[68:71]
	v_mfma_f32_16x16x32_bf16 v[64:67], v[226:229], v[210:213], v[64:67]
	v_mfma_f32_16x16x32_bf16 v[116:119], v[222:225], v[178:181], v[116:119]
	v_mfma_f32_16x16x32_bf16 v[112:115], v[230:233], v[178:181], v[112:115]
	v_mfma_f32_16x16x32_bf16 v[100:103], v[222:225], v[186:189], v[100:103]
	v_mfma_f32_16x16x32_bf16 v[96:99], v[230:233], v[186:189], v[96:99]
	v_mfma_f32_16x16x32_bf16 v[84:87], v[222:225], v[206:209], v[84:87]
	v_mfma_f32_16x16x32_bf16 v[80:83], v[230:233], v[206:209], v[80:83]
	v_mfma_f32_16x16x32_bf16 v[68:71], v[222:225], v[214:217], v[68:71]
	v_mfma_f32_16x16x32_bf16 v[64:67], v[230:233], v[214:217], v[64:67]
	s_barrier
	s_mov_b32 m0, s53
	ds_read_b128 v[174:177], v168 offset:49152
	ds_read_b128 v[178:181], v168 offset:50176
	ds_read_b128 v[182:185], v168 offset:51200
	ds_read_b128 v[186:189], v168 offset:52224
	ds_read_b128 v[190:193], v168 offset:53248
	ds_read_b128 v[206:209], v168 offset:54272
	ds_read_b128 v[210:213], v168 offset:55296
	ds_read_b128 v[214:217], v168 offset:56320
	global_load_lds_dwordx4 v128, s[98:99]
	s_mov_b32 m0, s54
	s_nop 0
	global_load_lds_dwordx4 v132, s[98:99]
	s_barrier
	s_waitcnt lgkmcnt(0)
	v_mfma_f32_16x16x32_bf16 v[60:63], v[140:143], v[174:177], v[60:63]
	v_mfma_f32_16x16x32_bf16 v[56:59], v[148:151], v[174:177], v[56:59]
	v_mfma_f32_16x16x32_bf16 v[48:51], v[140:143], v[182:185], v[48:51]
	v_mfma_f32_16x16x32_bf16 v[40:43], v[148:151], v[182:185], v[40:43]
	v_mfma_f32_16x16x32_bf16 v[32:35], v[140:143], v[190:193], v[32:35]
	v_mfma_f32_16x16x32_bf16 v[24:27], v[148:151], v[190:193], v[24:27]
	v_mfma_f32_16x16x32_bf16 v[16:19], v[140:143], v[210:213], v[16:19]
	v_mfma_f32_16x16x32_bf16 v[8:11], v[148:151], v[210:213], v[8:11]
	v_mfma_f32_16x16x32_bf16 v[60:63], v[144:147], v[178:181], v[60:63]
	v_mfma_f32_16x16x32_bf16 v[56:59], v[170:173], v[178:181], v[56:59]
	v_mfma_f32_16x16x32_bf16 v[48:51], v[144:147], v[186:189], v[48:51]
	v_mfma_f32_16x16x32_bf16 v[40:43], v[170:173], v[186:189], v[40:43]
	v_mfma_f32_16x16x32_bf16 v[32:35], v[144:147], v[206:209], v[32:35]
	v_mfma_f32_16x16x32_bf16 v[24:27], v[170:173], v[206:209], v[24:27]
	v_mfma_f32_16x16x32_bf16 v[16:19], v[144:147], v[214:217], v[16:19]
	v_mfma_f32_16x16x32_bf16 v[8:11], v[170:173], v[214:217], v[8:11]
	s_barrier
	s_add_u32 s22, s22, 0x80080
	s_addc_u32 s23, s23, 0
	s_add_i32 s42, s42, s48
	s_mov_b32 m0, s42
	s_nop 0
	global_load_lds_dwordx4 v130, s[22:23]
	s_add_i32 m0, s42, 0x2000
	s_nop 0
	global_load_lds_dwordx4 v134, s[22:23]
	s_add_i32 s58, s58, 2
	s_add_u32 s20, s20, 0x100
	s_addc_u32 s21, s21, 0
	s_add_u32 s35, s35, 0x100
	s_addc_u32 s57, s57, 0
	s_add_u32 s22, s20, 0xfff80080
	s_addc_u32 s23, s21, -1
	s_add_i32 s59, 0, 0x10000
	s_cmp_eq_u32 s58, 28
	s_cselect_b32 s43, s5, s23
	s_cselect_b32 s42, s6, s22
	s_cselect_b32 s23, s7, s57
	s_cselect_b32 s22, s25, s35
	s_add_i32 m0, s49, 0xc000
	s_cmp_gt_u32 s58, 29
	s_waitcnt vmcnt(6)
	s_barrier
	v_mfma_f32_16x16x32_bf16 v[52:55], v[218:221], v[174:177], v[52:55]
	v_mfma_f32_16x16x32_bf16 v[44:47], v[226:229], v[174:177], v[44:47]
	v_mfma_f32_16x16x32_bf16 v[36:39], v[218:221], v[182:185], v[36:39]
	v_mfma_f32_16x16x32_bf16 v[28:31], v[226:229], v[182:185], v[28:31]
	v_mfma_f32_16x16x32_bf16 v[20:23], v[218:221], v[190:193], v[20:23]
	v_mfma_f32_16x16x32_bf16 v[12:15], v[226:229], v[190:193], v[12:15]
	v_mfma_f32_16x16x32_bf16 v[4:7], v[218:221], v[210:213], v[4:7]
	v_mfma_f32_16x16x32_bf16 v[0:3], v[226:229], v[210:213], v[0:3]
	v_mfma_f32_16x16x32_bf16 v[52:55], v[222:225], v[178:181], v[52:55]
	v_mfma_f32_16x16x32_bf16 v[44:47], v[230:233], v[178:181], v[44:47]
	v_mfma_f32_16x16x32_bf16 v[36:39], v[222:225], v[186:189], v[36:39]
	v_mfma_f32_16x16x32_bf16 v[28:31], v[230:233], v[186:189], v[28:31]
	v_mfma_f32_16x16x32_bf16 v[20:23], v[222:225], v[206:209], v[20:23]
	v_mfma_f32_16x16x32_bf16 v[12:15], v[230:233], v[206:209], v[12:15]
	v_mfma_f32_16x16x32_bf16 v[4:7], v[222:225], v[214:217], v[4:7]
	v_mfma_f32_16x16x32_bf16 v[0:3], v[230:233], v[214:217], v[0:3]
	s_barrier
	s_cbranch_scc0 .LBB0_227
	s_cmpk_gt_u32 s14, 0xff
	s_cbranch_scc1 .Lal_e0_p
	s_barrier
.Lal_e0_p:
	v_lshl_add_u32 v140, s4, 8, v164
	s_cmp_gt_i32 s56, 23
	s_mov_b64 s[20:21], -1
	s_cbranch_scc1 .LBB0_262
	s_cmp_lt_i32 s56, 4
	s_cselect_b64 s[4:5], -1, 0
	s_and_b32 s6, s56, 0x7ffffffc
	s_cmp_eq_u32 s6, 16
	s_cselect_b64 s[6:7], -1, 0
	s_or_b64 s[20:21], s[4:5], s[6:7]
	s_and_b64 vcc, exec, s[20:21]
	v_mov_b32_e32 v149, v123
	v_mov_b32_e32 v148, v122
	v_mov_b32_e32 v163, v121
	v_mov_b32_e32 v162, v120
	v_mov_b32_e32 v147, v127
	v_mov_b32_e32 v146, v126
	v_mov_b32_e32 v151, v125
	v_mov_b32_e32 v150, v124
	s_cbranch_vccz .LBB0_231
	v_mul_f32_e32 v141, 0xbfb8aa3b, v124
	v_exp_f32_e32 v141, v141
	v_mul_f32_e32 v142, 0xbfb8aa3b, v120
	v_mul_f32_e32 v145, 0xbfb8aa3b, v126
	v_mul_f32_e32 v143, 0xbfb8aa3b, v125
	v_exp_f32_e32 v144, v142
	v_exp_f32_e32 v145, v145
	v_mul_f32_e32 v146, 0xbfb8aa3b, v122
	v_exp_f32_e32 v143, v143
	v_exp_f32_e32 v147, v146
	v_add_f32_e32 v141, 1.0, v141
	v_rcp_f32_e32 v142, v141
	v_add_f32_e32 v141, 1.0, v144
	v_add_f32_e32 v145, 1.0, v145
	v_rcp_f32_e32 v144, v141
	v_add_f32_e32 v141, 1.0, v143
	v_rcp_f32_e32 v146, v145
	v_add_f32_e32 v145, 1.0, v147
	v_mul_f32_e32 v147, 0xbfb8aa3b, v127
	v_rcp_f32_e32 v143, v141
	v_mul_f32_e32 v141, 0xbfb8aa3b, v121
	v_exp_f32_e32 v147, v147
	v_mul_f32_e32 v148, 0xbfb8aa3b, v123
	v_exp_f32_e32 v141, v141
	v_exp_f32_e32 v149, v148
	v_rcp_f32_e32 v148, v145
	v_add_f32_e32 v145, 1.0, v147
	v_add_f32_e32 v141, 1.0, v141
	v_rcp_f32_e32 v147, v145
	v_add_f32_e32 v145, 1.0, v149
	v_rcp_f32_e32 v149, v145
	v_rcp_f32_e32 v145, v141
	v_pk_mul_f32 v[146:147], v[126:127], v[146:147]
	v_pk_mul_f32 v[150:151], v[124:125], v[142:143]
	v_pk_mul_f32 v[148:149], v[122:123], v[148:149]
	v_pk_mul_f32 v[162:163], v[120:121], v[144:145]

.LBB0_264:
	s_waitcnt vmcnt(0)
	v_readlane_b32 s34, v253, 45
	s_cmpk_gt_u32 s14, 0xff
	v_readlane_b32 s35, v253, 46
	s_cbranch_scc1 .LBB0_266
.LBB0_266:
	s_barrier

.LBB0_560:
	s_ashr_i32 s17, s16, 31
	s_lshl_b64 s[6:7], s[16:17], 20
	v_cmp_lt_i64_e32 vcc, s[24:25], v[160:161]
	s_add_u32 s24, s56, s6
	s_addc_u32 s25, s57, s7
	s_and_b64 s[6:7], vcc, exec
	s_cselect_b32 s5, s25, s23
	s_cselect_b32 s6, s24, s22
	s_ashr_i32 s1, s0, 31
	s_lshl_b64 s[34:35], s[0:1], 20
	s_add_u32 s34, s58, s34
	s_addc_u32 s35, s59, s35
	s_and_b64 s[52:53], vcc, exec
	s_cselect_b32 s1, s35, s39
	s_cselect_b32 s7, s34, s38
	s_add_u32 s22, s22, 0x80080
	s_addc_u32 s23, s23, 0
	s_add_u32 s17, s38, 0x100
	v_mov_b32_e32 v0, 0
	s_addc_u32 s21, s39, 0
	s_mov_b32 s30, -2
	v_mov_b32_e32 v1, v0
	v_mov_b32_e32 v2, v0
	v_mov_b32_e32 v3, v0
	v_mov_b32_e32 v4, v0
	v_mov_b32_e32 v5, v0
	v_mov_b32_e32 v6, v0
	v_mov_b32_e32 v7, v0
	v_mov_b32_e32 v16, v0
	v_mov_b32_e32 v17, v0
	v_mov_b32_e32 v18, v0
	v_mov_b32_e32 v19, v0
	v_mov_b32_e32 v20, v0
	v_mov_b32_e32 v21, v0
	v_mov_b32_e32 v22, v0
	v_mov_b32_e32 v23, v0
	v_mov_b32_e32 v32, v0
	v_mov_b32_e32 v33, v0
	v_mov_b32_e32 v34, v0
	v_mov_b32_e32 v35, v0
	v_mov_b32_e32 v36, v0
	v_mov_b32_e32 v37, v0
	v_mov_b32_e32 v38, v0
	v_mov_b32_e32 v39, v0
	v_mov_b32_e32 v48, v0
	v_mov_b32_e32 v49, v0
	v_mov_b32_e32 v50, v0
	v_mov_b32_e32 v51, v0
	v_mov_b32_e32 v52, v0
	v_mov_b32_e32 v53, v0
	v_mov_b32_e32 v54, v0
	v_mov_b32_e32 v55, v0
	v_mov_b32_e32 v8, v0
	v_mov_b32_e32 v9, v0
	v_mov_b32_e32 v10, v0
	v_mov_b32_e32 v11, v0
	v_mov_b32_e32 v12, v0
	v_mov_b32_e32 v13, v0
	v_mov_b32_e32 v14, v0
	v_mov_b32_e32 v15, v0
	v_mov_b32_e32 v24, v0
	v_mov_b32_e32 v25, v0
	v_mov_b32_e32 v26, v0
	v_mov_b32_e32 v27, v0
	v_mov_b32_e32 v28, v0
	v_mov_b32_e32 v29, v0
	v_mov_b32_e32 v30, v0
	v_mov_b32_e32 v31, v0
	v_mov_b32_e32 v40, v0
	v_mov_b32_e32 v41, v0
	v_mov_b32_e32 v42, v0
	v_mov_b32_e32 v43, v0
	v_mov_b32_e32 v44, v0
	v_mov_b32_e32 v45, v0
	v_mov_b32_e32 v46, v0
	v_mov_b32_e32 v47, v0
	v_mov_b32_e32 v56, v0
	v_mov_b32_e32 v57, v0
	v_mov_b32_e32 v58, v0
	v_mov_b32_e32 v59, v0
	v_mov_b32_e32 v60, v0
	v_mov_b32_e32 v61, v0
	v_mov_b32_e32 v62, v0
	v_mov_b32_e32 v63, v0
	v_mov_b32_e32 v64, v0
	v_mov_b32_e32 v65, v0
	v_mov_b32_e32 v66, v0
	v_mov_b32_e32 v67, v0
	v_mov_b32_e32 v68, v0
	v_mov_b32_e32 v69, v0
	v_mov_b32_e32 v70, v0
	v_mov_b32_e32 v71, v0
	v_mov_b32_e32 v96, v0
	v_mov_b32_e32 v97, v0
	v_mov_b32_e32 v98, v0
	v_mov_b32_e32 v99, v0
	v_mov_b32_e32 v100, v0
	v_mov_b32_e32 v101, v0
	v_mov_b32_e32 v102, v0
	v_mov_b32_e32 v103, v0
	v_mov_b32_e32 v112, v0
	v_mov_b32_e32 v113, v0
	v_mov_b32_e32 v114, v0
	v_mov_b32_e32 v115, v0
	v_mov_b32_e32 v116, v0
	v_mov_b32_e32 v117, v0
	v_mov_b32_e32 v118, v0
	v_mov_b32_e32 v119, v0
	v_mov_b32_e32 v128, v0
	v_mov_b32_e32 v129, v0
	v_mov_b32_e32 v130, v0
	v_mov_b32_e32 v131, v0
	v_mov_b32_e32 v132, v0
	v_mov_b32_e32 v133, v0
	v_mov_b32_e32 v134, v0
	v_mov_b32_e32 v135, v0
	v_mov_b32_e32 v80, v0
	v_mov_b32_e32 v81, v0
	v_mov_b32_e32 v82, v0
	v_mov_b32_e32 v83, v0
	v_mov_b32_e32 v88, v0
	v_mov_b32_e32 v89, v0
	v_mov_b32_e32 v90, v0
	v_mov_b32_e32 v91, v0
	v_mov_b32_e32 v104, v0
	v_mov_b32_e32 v105, v0
	v_mov_b32_e32 v106, v0
	v_mov_b32_e32 v107, v0
	v_mov_b32_e32 v108, v0
	v_mov_b32_e32 v109, v0
	v_mov_b32_e32 v110, v0
	v_mov_b32_e32 v111, v0
	v_mov_b32_e32 v120, v0
	v_mov_b32_e32 v121, v0
	v_mov_b32_e32 v122, v0
	v_mov_b32_e32 v123, v0
	v_mov_b32_e32 v124, v0
	v_mov_b32_e32 v125, v0
	v_mov_b32_e32 v126, v0
	v_mov_b32_e32 v127, v0
	v_mov_b32_e32 v136, v0
	v_mov_b32_e32 v137, v0
	v_mov_b32_e32 v138, v0
	v_mov_b32_e32 v139, v0
	v_mov_b32_e32 v140, v0
	v_mov_b32_e32 v141, v0
	v_mov_b32_e32 v142, v0
	v_mov_b32_e32 v143, v0
	s_cmpk_lt_u32 s15, 0x100
	s_cbranch_scc1 .Lal_e1_w
	s_cmp_lt_u32 s83, 2
	s_cbranch_scc1 .Lal_e1_w
	s_barrier
.Lal_e1_w:
	v_add_u32_e32 v246, 0x10000, v206
	v_add_u32_e32 v247, 0x14000, v206
	v_add_u32_e32 v248, 0x18000, v206
	v_add_u32_e32 v249, 0x1c000, v206
	s_add_u32 s38, s22, 0xfff80080
	s_addc_u32 s39, s23, -1
	s_add_i32 s84, 0, 0x10000
	s_cmp_eq_u32 s30, 28
	s_cselect_b32 s53, s5, s39
	s_cselect_b32 s52, s6, s38
	s_cselect_b32 s39, s1, s21
	s_cselect_b32 s38, s7, s17
	s_add_i32 m0, s61, 0xc000
.LBB0_561:
	ds_read_b128 v[72:75], v246
	ds_read_b128 v[76:79], v246 offset:1024
	ds_read_b128 v[84:87], v246 offset:2048
	ds_read_b128 v[92:95], v246 offset:3072
	ds_read_b128 v[144:147], v208
	ds_read_b128 v[148:151], v208 offset:1024
	ds_read_b128 v[188:191], v208 offset:2048
	ds_read_b128 v[210:213], v208 offset:3072
	ds_read_b128 v[214:217], v208 offset:4096
	ds_read_b128 v[218:221], v208 offset:5120
	ds_read_b128 v[222:225], v208 offset:6144
	ds_read_b128 v[226:229], v208 offset:7168
	global_load_lds_dwordx4 v184, s[22:23]
	s_add_i32 m0, s61, 0xe000
	s_nop 0
	global_load_lds_dwordx4 v186, s[22:23]
	s_waitcnt lgkmcnt(8)
	s_barrier
	s_waitcnt lgkmcnt(0)
	v_mfma_f32_16x16x32_bf16 v[140:143], v[72:75], v[144:147], v[140:143]
	v_mfma_f32_16x16x32_bf16 v[136:139], v[84:87], v[144:147], v[136:139]
	v_mfma_f32_16x16x32_bf16 v[124:127], v[72:75], v[188:191], v[124:127]
	v_mfma_f32_16x16x32_bf16 v[120:123], v[84:87], v[188:191], v[120:123]
	v_mfma_f32_16x16x32_bf16 v[108:111], v[72:75], v[214:217], v[108:111]
	v_mfma_f32_16x16x32_bf16 v[104:107], v[84:87], v[214:217], v[104:107]
	v_mfma_f32_16x16x32_bf16 v[88:91], v[72:75], v[222:225], v[88:91]
	v_mfma_f32_16x16x32_bf16 v[80:83], v[84:87], v[222:225], v[80:83]
	v_mfma_f32_16x16x32_bf16 v[140:143], v[76:79], v[148:151], v[140:143]
	v_mfma_f32_16x16x32_bf16 v[136:139], v[92:95], v[148:151], v[136:139]
	v_mfma_f32_16x16x32_bf16 v[124:127], v[76:79], v[210:213], v[124:127]
	v_mfma_f32_16x16x32_bf16 v[120:123], v[92:95], v[210:213], v[120:123]
	v_mfma_f32_16x16x32_bf16 v[108:111], v[76:79], v[218:221], v[108:111]
	v_mfma_f32_16x16x32_bf16 v[104:107], v[92:95], v[218:221], v[104:107]
	v_mfma_f32_16x16x32_bf16 v[88:91], v[76:79], v[226:229], v[88:91]
	v_mfma_f32_16x16x32_bf16 v[80:83], v[92:95], v[226:229], v[80:83]
	s_barrier
	s_add_i32 s86, 0, 0x14000
	s_add_i32 s84, s84, s60
	ds_read_b128 v[230:233], v247
	ds_read_b128 v[234:237], v247 offset:1024
	ds_read_b128 v[238:241], v247 offset:2048
	ds_read_b128 v[242:245], v247 offset:3072
	s_mov_b32 m0, s84
	s_nop 0
	global_load_lds_dwordx4 v152, s[38:39]
	s_add_i32 m0, s84, 0x2000
	s_nop 0
	global_load_lds_dwordx4 v162, s[38:39]
	s_barrier
	s_waitcnt lgkmcnt(0)
	v_mfma_f32_16x16x32_bf16 v[132:135], v[230:233], v[144:147], v[132:135]
	v_mfma_f32_16x16x32_bf16 v[128:131], v[238:241], v[144:147], v[128:131]
	v_mfma_f32_16x16x32_bf16 v[116:119], v[230:233], v[188:191], v[116:119]
	v_mfma_f32_16x16x32_bf16 v[112:115], v[238:241], v[188:191], v[112:115]
	v_mfma_f32_16x16x32_bf16 v[100:103], v[230:233], v[214:217], v[100:103]
	v_mfma_f32_16x16x32_bf16 v[96:99], v[238:241], v[214:217], v[96:99]
	v_mfma_f32_16x16x32_bf16 v[68:71], v[230:233], v[222:225], v[68:71]
	v_mfma_f32_16x16x32_bf16 v[64:67], v[238:241], v[222:225], v[64:67]
	v_mfma_f32_16x16x32_bf16 v[132:135], v[234:237], v[148:151], v[132:135]
	v_mfma_f32_16x16x32_bf16 v[128:131], v[242:245], v[148:151], v[128:131]
	v_mfma_f32_16x16x32_bf16 v[116:119], v[234:237], v[210:213], v[116:119]
	v_mfma_f32_16x16x32_bf16 v[112:115], v[242:245], v[210:213], v[112:115]
	v_mfma_f32_16x16x32_bf16 v[100:103], v[234:237], v[218:221], v[100:103]
	v_mfma_f32_16x16x32_bf16 v[96:99], v[242:245], v[218:221], v[96:99]
	v_mfma_f32_16x16x32_bf16 v[68:71], v[234:237], v[226:229], v[68:71]
	v_mfma_f32_16x16x32_bf16 v[64:67], v[242:245], v[226:229], v[64:67]
	s_barrier
	s_mov_b32 m0, s61
	s_add_u32 s98, s52, 0x80
	s_addc_u32 s99, s53, 0
	ds_read_b128 v[144:147], v208 offset:16384
	ds_read_b128 v[148:151], v208 offset:17408
	ds_read_b128 v[188:191], v208 offset:18432
	ds_read_b128 v[210:213], v208 offset:19456
	ds_read_b128 v[214:217], v208 offset:20480
	ds_read_b128 v[218:221], v208 offset:21504
	ds_read_b128 v[222:225], v208 offset:22528
	ds_read_b128 v[226:229], v208 offset:23552
	global_load_lds_dwordx4 v166, s[52:53]
	s_mov_b32 m0, s62
	s_nop 0
	global_load_lds_dwordx4 v164, s[52:53]
	s_barrier
	s_waitcnt lgkmcnt(0)
	v_mfma_f32_16x16x32_bf16 v[60:63], v[72:75], v[144:147], v[60:63]
	v_mfma_f32_16x16x32_bf16 v[56:59], v[84:87], v[144:147], v[56:59]
	v_mfma_f32_16x16x32_bf16 v[44:47], v[72:75], v[188:191], v[44:47]
	v_mfma_f32_16x16x32_bf16 v[40:43], v[84:87], v[188:191], v[40:43]
	v_mfma_f32_16x16x32_bf16 v[28:31], v[72:75], v[214:217], v[28:31]
	v_mfma_f32_16x16x32_bf16 v[24:27], v[84:87], v[214:217], v[24:27]
	v_mfma_f32_16x16x32_bf16 v[12:15], v[72:75], v[222:225], v[12:15]
	v_mfma_f32_16x16x32_bf16 v[8:11], v[84:87], v[222:225], v[8:11]
	v_mfma_f32_16x16x32_bf16 v[60:63], v[76:79], v[148:151], v[60:63]
	v_mfma_f32_16x16x32_bf16 v[56:59], v[92:95], v[148:151], v[56:59]
	v_mfma_f32_16x16x32_bf16 v[44:47], v[76:79], v[210:213], v[44:47]
	v_mfma_f32_16x16x32_bf16 v[40:43], v[92:95], v[210:213], v[40:43]
	v_mfma_f32_16x16x32_bf16 v[28:31], v[76:79], v[218:221], v[28:31]
	v_mfma_f32_16x16x32_bf16 v[24:27], v[92:95], v[218:221], v[24:27]
	v_mfma_f32_16x16x32_bf16 v[12:15], v[76:79], v[226:229], v[12:15]
	v_mfma_f32_16x16x32_bf16 v[8:11], v[92:95], v[226:229], v[8:11]
	s_barrier
	s_add_u32 s84, s38, 0x80000
	s_addc_u32 s85, s39, 0
	s_add_i32 s86, s86, s60
	s_mov_b32 m0, s86
	s_nop 0
	global_load_lds_dwordx4 v152, s[84:85]
	s_add_i32 m0, s86, 0x2000
	s_nop 0
	global_load_lds_dwordx4 v162, s[84:85]
	s_add_i32 s84, 0, 0x18000
	s_add_u32 s52, s52, 0x80000
	s_addc_u32 s53, s53, 0
	s_mov_b32 m0, s63
	s_waitcnt vmcnt(6)
	s_barrier
	v_mfma_f32_16x16x32_bf16 v[52:55], v[230:233], v[144:147], v[52:55]
	v_mfma_f32_16x16x32_bf16 v[48:51], v[238:241], v[144:147], v[48:51]
	v_mfma_f32_16x16x32_bf16 v[36:39], v[230:233], v[188:191], v[36:39]
	v_mfma_f32_16x16x32_bf16 v[32:35], v[238:241], v[188:191], v[32:35]
	v_mfma_f32_16x16x32_bf16 v[20:23], v[230:233], v[214:217], v[20:23]
	v_mfma_f32_16x16x32_bf16 v[16:19], v[238:241], v[214:217], v[16:19]
	v_mfma_f32_16x16x32_bf16 v[4:7], v[230:233], v[222:225], v[4:7]
	v_mfma_f32_16x16x32_bf16 v[0:3], v[238:241], v[222:225], v[0:3]
	v_mfma_f32_16x16x32_bf16 v[52:55], v[234:237], v[148:151], v[52:55]
	v_mfma_f32_16x16x32_bf16 v[48:51], v[242:245], v[148:151], v[48:51]
	v_mfma_f32_16x16x32_bf16 v[36:39], v[234:237], v[210:213], v[36:39]
	v_mfma_f32_16x16x32_bf16 v[32:35], v[242:245], v[210:213], v[32:35]
	v_mfma_f32_16x16x32_bf16 v[20:23], v[234:237], v[218:221], v[20:23]
	v_mfma_f32_16x16x32_bf16 v[16:19], v[242:245], v[218:221], v[16:19]
	v_mfma_f32_16x16x32_bf16 v[4:7], v[234:237], v[226:229], v[4:7]
	v_mfma_f32_16x16x32_bf16 v[0:3], v[242:245], v[226:229], v[0:3]
	s_barrier
	ds_read_b128 v[72:75], v248
	ds_read_b128 v[76:79], v248 offset:1024
	ds_read_b128 v[84:87], v248 offset:2048
	ds_read_b128 v[92:95], v248 offset:3072
	ds_read_b128 v[144:147], v208 offset:32768
	ds_read_b128 v[148:151], v208 offset:33792
	ds_read_b128 v[188:191], v208 offset:34816
	ds_read_b128 v[210:213], v208 offset:35840
	ds_read_b128 v[214:217], v208 offset:36864
	ds_read_b128 v[218:221], v208 offset:37888
	ds_read_b128 v[222:225], v208 offset:38912
	ds_read_b128 v[226:229], v208 offset:39936
	global_load_lds_dwordx4 v166, s[52:53]
	s_mov_b32 m0, s68
	s_nop 0
	global_load_lds_dwordx4 v164, s[52:53]
	s_waitcnt lgkmcnt(8)
	s_barrier
	s_waitcnt lgkmcnt(0)
	v_mfma_f32_16x16x32_bf16 v[140:143], v[72:75], v[144:147], v[140:143]
	v_mfma_f32_16x16x32_bf16 v[136:139], v[84:87], v[144:147], v[136:139]
	v_mfma_f32_16x16x32_bf16 v[124:127], v[72:75], v[188:191], v[124:127]
	v_mfma_f32_16x16x32_bf16 v[120:123], v[84:87], v[188:191], v[120:123]
	v_mfma_f32_16x16x32_bf16 v[108:111], v[72:75], v[214:217], v[108:111]
	v_mfma_f32_16x16x32_bf16 v[104:107], v[84:87], v[214:217], v[104:107]
	v_mfma_f32_16x16x32_bf16 v[88:91], v[72:75], v[222:225], v[88:91]
	v_mfma_f32_16x16x32_bf16 v[80:83], v[84:87], v[222:225], v[80:83]
	v_mfma_f32_16x16x32_bf16 v[140:143], v[76:79], v[148:151], v[140:143]
	v_mfma_f32_16x16x32_bf16 v[136:139], v[92:95], v[148:151], v[136:139]
	v_mfma_f32_16x16x32_bf16 v[124:127], v[76:79], v[210:213], v[124:127]
	v_mfma_f32_16x16x32_bf16 v[120:123], v[92:95], v[210:213], v[120:123]
	v_mfma_f32_16x16x32_bf16 v[108:111], v[76:79], v[218:221], v[108:111]
	v_mfma_f32_16x16x32_bf16 v[104:107], v[92:95], v[218:221], v[104:107]
	v_mfma_f32_16x16x32_bf16 v[88:91], v[76:79], v[226:229], v[88:91]
	v_mfma_f32_16x16x32_bf16 v[80:83], v[92:95], v[226:229], v[80:83]
	s_barrier
	s_add_i32 s52, 0, 0x1c000
	s_add_i32 s53, s84, s60
	s_add_u32 s100, s38, 0x80
	s_addc_u32 s101, s39, 0
	s_mov_b32 m0, s53
	ds_read_b128 v[230:233], v249
	ds_read_b128 v[234:237], v249 offset:1024
	ds_read_b128 v[238:241], v249 offset:2048
	ds_read_b128 v[242:245], v249 offset:3072
	global_load_lds_dwordx4 v152, s[100:101]
	s_add_i32 m0, s53, 0x2000
	s_nop 0
	global_load_lds_dwordx4 v162, s[100:101]
	s_barrier
	s_waitcnt lgkmcnt(0)
	v_mfma_f32_16x16x32_bf16 v[132:135], v[230:233], v[144:147], v[132:135]
	v_mfma_f32_16x16x32_bf16 v[128:131], v[238:241], v[144:147], v[128:131]
	v_mfma_f32_16x16x32_bf16 v[116:119], v[230:233], v[188:191], v[116:119]
	v_mfma_f32_16x16x32_bf16 v[112:115], v[238:241], v[188:191], v[112:115]
	v_mfma_f32_16x16x32_bf16 v[100:103], v[230:233], v[214:217], v[100:103]
	v_mfma_f32_16x16x32_bf16 v[96:99], v[238:241], v[214:217], v[96:99]
	v_mfma_f32_16x16x32_bf16 v[68:71], v[230:233], v[222:225], v[68:71]
	v_mfma_f32_16x16x32_bf16 v[64:67], v[238:241], v[222:225], v[64:67]
	v_mfma_f32_16x16x32_bf16 v[132:135], v[234:237], v[148:151], v[132:135]
	v_mfma_f32_16x16x32_bf16 v[128:131], v[242:245], v[148:151], v[128:131]
	v_mfma_f32_16x16x32_bf16 v[116:119], v[234:237], v[210:213], v[116:119]
	v_mfma_f32_16x16x32_bf16 v[112:115], v[242:245], v[210:213], v[112:115]
	v_mfma_f32_16x16x32_bf16 v[100:103], v[234:237], v[218:221], v[100:103]
	v_mfma_f32_16x16x32_bf16 v[96:99], v[242:245], v[218:221], v[96:99]
	v_mfma_f32_16x16x32_bf16 v[68:71], v[234:237], v[226:229], v[68:71]
	v_mfma_f32_16x16x32_bf16 v[64:67], v[242:245], v[226:229], v[64:67]
	s_barrier
	s_mov_b32 m0, s81
	ds_read_b128 v[144:147], v208 offset:49152
	ds_read_b128 v[148:151], v208 offset:50176
	ds_read_b128 v[188:191], v208 offset:51200
	ds_read_b128 v[210:213], v208 offset:52224
	ds_read_b128 v[214:217], v208 offset:53248
	ds_read_b128 v[218:221], v208 offset:54272
	ds_read_b128 v[222:225], v208 offset:55296
	ds_read_b128 v[226:229], v208 offset:56320
	global_load_lds_dwordx4 v166, s[98:99]
	s_mov_b32 m0, s82
	s_nop 0
	global_load_lds_dwordx4 v164, s[98:99]
	s_barrier
	s_waitcnt lgkmcnt(0)
	v_mfma_f32_16x16x32_bf16 v[60:63], v[72:75], v[144:147], v[60:63]
	v_mfma_f32_16x16x32_bf16 v[56:59], v[84:87], v[144:147], v[56:59]
	v_mfma_f32_16x16x32_bf16 v[44:47], v[72:75], v[188:191], v[44:47]
	v_mfma_f32_16x16x32_bf16 v[40:43], v[84:87], v[188:191], v[40:43]
	v_mfma_f32_16x16x32_bf16 v[28:31], v[72:75], v[214:217], v[28:31]
	v_mfma_f32_16x16x32_bf16 v[24:27], v[84:87], v[214:217], v[24:27]
	v_mfma_f32_16x16x32_bf16 v[12:15], v[72:75], v[222:225], v[12:15]
	v_mfma_f32_16x16x32_bf16 v[8:11], v[84:87], v[222:225], v[8:11]
	v_mfma_f32_16x16x32_bf16 v[60:63], v[76:79], v[148:151], v[60:63]
	v_mfma_f32_16x16x32_bf16 v[56:59], v[92:95], v[148:151], v[56:59]
	v_mfma_f32_16x16x32_bf16 v[44:47], v[76:79], v[210:213], v[44:47]
	v_mfma_f32_16x16x32_bf16 v[40:43], v[92:95], v[210:213], v[40:43]
	v_mfma_f32_16x16x32_bf16 v[28:31], v[76:79], v[218:221], v[28:31]
	v_mfma_f32_16x16x32_bf16 v[24:27], v[92:95], v[218:221], v[24:27]
	v_mfma_f32_16x16x32_bf16 v[12:15], v[76:79], v[226:229], v[12:15]
	v_mfma_f32_16x16x32_bf16 v[8:11], v[92:95], v[226:229], v[8:11]
	s_barrier
	s_add_u32 s38, s38, 0x80080
	s_addc_u32 s39, s39, 0
	s_add_i32 s52, s52, s60
	s_mov_b32 m0, s52
	s_nop 0
	global_load_lds_dwordx4 v152, s[38:39]
	s_add_i32 m0, s52, 0x2000
	s_nop 0
	global_load_lds_dwordx4 v162, s[38:39]
	s_add_i32 s30, s30, 2
	s_add_u32 s22, s22, 0x100
	s_addc_u32 s23, s23, 0
	s_add_u32 s17, s17, 0x100
	s_addc_u32 s21, s21, 0
	s_add_u32 s38, s22, 0xfff80080
	s_addc_u32 s39, s23, -1
	s_add_i32 s84, 0, 0x10000
	s_cmp_eq_u32 s30, 28
	s_cselect_b32 s53, s5, s39
	s_cselect_b32 s52, s6, s38
	s_cselect_b32 s39, s1, s21
	s_cselect_b32 s38, s7, s17
	s_add_i32 m0, s61, 0xc000
	s_cmp_gt_u32 s30, 29
	s_waitcnt vmcnt(6)
	s_barrier
	v_mfma_f32_16x16x32_bf16 v[52:55], v[230:233], v[144:147], v[52:55]
	v_mfma_f32_16x16x32_bf16 v[48:51], v[238:241], v[144:147], v[48:51]
	v_mfma_f32_16x16x32_bf16 v[36:39], v[230:233], v[188:191], v[36:39]
	v_mfma_f32_16x16x32_bf16 v[32:35], v[238:241], v[188:191], v[32:35]
	v_mfma_f32_16x16x32_bf16 v[20:23], v[230:233], v[214:217], v[20:23]
	v_mfma_f32_16x16x32_bf16 v[16:19], v[238:241], v[214:217], v[16:19]
	v_mfma_f32_16x16x32_bf16 v[4:7], v[230:233], v[222:225], v[4:7]
	v_mfma_f32_16x16x32_bf16 v[0:3], v[238:241], v[222:225], v[0:3]
	v_mfma_f32_16x16x32_bf16 v[52:55], v[234:237], v[148:151], v[52:55]
	v_mfma_f32_16x16x32_bf16 v[48:51], v[242:245], v[148:151], v[48:51]
	v_mfma_f32_16x16x32_bf16 v[36:39], v[234:237], v[210:213], v[36:39]
	v_mfma_f32_16x16x32_bf16 v[32:35], v[242:245], v[210:213], v[32:35]
	v_mfma_f32_16x16x32_bf16 v[20:23], v[234:237], v[218:221], v[20:23]
	v_mfma_f32_16x16x32_bf16 v[16:19], v[242:245], v[218:221], v[16:19]
	v_mfma_f32_16x16x32_bf16 v[4:7], v[234:237], v[226:229], v[4:7]
	v_mfma_f32_16x16x32_bf16 v[0:3], v[242:245], v[226:229], v[0:3]
	s_barrier
	s_cbranch_scc0 .LBB0_561
	s_cmpk_gt_u32 s15, 0xff
	s_cbranch_scc1 .Lal_e0_w
	s_barrier
.Lal_e0_w:
	v_lshl_or_b32 v188, s4, 8, v207
	v_ashrrev_i32_e32 v189, 31, v188
	s_cmp_lt_i32 s20, 16
	s_cselect_b32 s6, s44, s46
	s_cselect_b32 s7, s45, s47
	s_cselect_b32 s1, 0, 16
	s_sub_i32 s4, s20, s1
	s_mov_b32 s5, 0
	s_lshl_b64 s[4:5], s[4:5], 21
	s_add_u32 s38, s6, s4
	s_addc_u32 s39, s7, s5
	s_cmp_lt_i32 s20, 32
	s_cselect_b32 s1, 0x3000, s73
	s_cmp_lt_i32 s20, 16
	s_cselect_b32 s1, 0, s1
	s_lshl_b32 s1, s1, 2
	s_add_u32 s6, s79, s1
	s_addc_u32 s7, s80, 0
	s_mov_b32 s4, s20
	s_mov_b32 s5, 0
	s_lshl_b64 s[4:5], s[4:5], 20
	s_add_u32 s52, s69, s4
	s_addc_u32 s53, s78, s5
	v_lshl_add_u64 v[190:191], v[188:189], 2, s[6:7]
	s_mov_b64 s[4:5], 0x28504000
	v_lshl_add_u64 v[190:191], v[190:191], 0, s[4:5]
	global_load_dwordx4 v[92:95], v[190:191], off
	global_load_dwordx4 v[84:87], v[190:191], off offset:16
	global_load_dwordx4 v[76:79], v[190:191], off offset:512
	global_load_dwordx4 v[72:75], v[190:191], off offset:528
	v_lshl_add_u64 v[144:145], v[188:189], 1, s[52:53]
	s_and_b64 vcc, exec, s[64:65]
	s_cbranch_vccz .Lwo_epi_f32
	v_lshl_add_u64 v[148:149], v[168:169], 1, v[144:145]
	global_load_dwordx4 v[210:213], v[148:149], off
	global_load_dwordx4 v[214:217], v[148:149], off offset:256
	v_lshl_add_u64 v[148:149], v[170:171], 1, v[144:145]
	global_load_dwordx4 v[218:221], v[148:149], off
	global_load_dwordx4 v[222:225], v[148:149], off offset:256
	v_lshl_add_u64 v[148:149], v[172:173], 1, v[144:145]
	global_load_dwordx4 v[226:229], v[148:149], off
	global_load_dwordx4 v[230:233], v[148:149], off offset:256
	v_lshl_add_u64 v[148:149], v[174:175], 1, v[144:145]
	global_load_dwordx4 v[234:237], v[148:149], off
	global_load_dwordx4 v[238:241], v[148:149], off offset:256
	v_lshl_add_u64 v[148:149], v[176:177], 1, v[144:145]
	global_load_dwordx4 v[242:245], v[148:149], off
	s_waitcnt vmcnt(8)
	v_lshlrev_b32_e32 v188, 16, v210
	v_and_b32_e32 v189, 0xffff0000, v210
	v_lshlrev_b32_e32 v190, 16, v211
	v_and_b32_e32 v191, 0xffff0000, v211
	v_lshlrev_b32_e32 v246, 16, v212
	v_and_b32_e32 v247, 0xffff0000, v212
	v_lshlrev_b32_e32 v248, 16, v213
	v_and_b32_e32 v249, 0xffff0000, v213
	global_load_dwordx4 v[210:213], v[148:149], off offset:256
	v_lshl_add_u64 v[150:151], v[168:169], 1, v[144:145]
	v_pk_fma_f32 v[140:141], v[140:141], v[92:93], v[188:189]
	v_pk_fma_f32 v[142:143], v[142:143], v[94:95], v[190:191]
	v_pk_fma_f32 v[136:137], v[136:137], v[84:85], v[246:247]
	v_pk_fma_f32 v[138:139], v[138:139], v[86:87], v[248:249]
	v_cvt_pk_bf16_f32 v140, v140, v141
	v_cvt_pk_bf16_f32 v141, v142, v143
	v_cvt_pk_bf16_f32 v142, v136, v137
	v_cvt_pk_bf16_f32 v143, v138, v139
	global_store_dwordx4 v[150:151], v[140:143], off
	s_waitcnt vmcnt(9)
	v_lshlrev_b32_e32 v188, 16, v214
	v_and_b32_e32 v189, 0xffff0000, v214
	v_lshlrev_b32_e32 v190, 16, v215
	v_and_b32_e32 v191, 0xffff0000, v215
	v_lshlrev_b32_e32 v246, 16, v216
	v_and_b32_e32 v247, 0xffff0000, v216
	v_lshlrev_b32_e32 v248, 16, v217
	v_and_b32_e32 v249, 0xffff0000, v217
	v_lshl_add_u64 v[148:149], v[178:179], 1, v[144:145]
	global_load_dwordx4 v[214:217], v[148:149], off
	v_pk_fma_f32 v[132:133], v[132:133], v[76:77], v[188:189]
	v_pk_fma_f32 v[134:135], v[134:135], v[78:79], v[190:191]
	v_pk_fma_f32 v[128:129], v[128:129], v[72:73], v[246:247]
	v_pk_fma_f32 v[130:131], v[130:131], v[74:75], v[248:249]
	v_cvt_pk_bf16_f32 v132, v132, v133
	v_cvt_pk_bf16_f32 v133, v134, v135
	v_cvt_pk_bf16_f32 v134, v128, v129
	v_cvt_pk_bf16_f32 v135, v130, v131
	global_store_dwordx4 v[150:151], v[132:135], off offset:256
	s_waitcnt vmcnt(10)
	v_lshlrev_b32_e32 v188, 16, v218
	v_and_b32_e32 v189, 0xffff0000, v218
	v_lshlrev_b32_e32 v190, 16, v219
	v_and_b32_e32 v191, 0xffff0000, v219
	v_lshlrev_b32_e32 v246, 16, v220
	v_and_b32_e32 v247, 0xffff0000, v220
	v_lshlrev_b32_e32 v248, 16, v221
	v_and_b32_e32 v249, 0xffff0000, v221
	global_load_dwordx4 v[218:221], v[148:149], off offset:256
	v_lshl_add_u64 v[192:193], v[170:171], 1, v[144:145]
	v_pk_fma_f32 v[124:125], v[124:125], v[92:93], v[188:189]
	v_pk_fma_f32 v[126:127], v[126:127], v[94:95], v[190:191]
	v_pk_fma_f32 v[120:121], v[120:121], v[84:85], v[246:247]
	v_pk_fma_f32 v[122:123], v[122:123], v[86:87], v[248:249]
	v_cvt_pk_bf16_f32 v124, v124, v125
	v_cvt_pk_bf16_f32 v125, v126, v127
	v_cvt_pk_bf16_f32 v126, v120, v121
	v_cvt_pk_bf16_f32 v127, v122, v123
	global_store_dwordx4 v[192:193], v[124:127], off
	s_waitcnt vmcnt(11)
	v_lshlrev_b32_e32 v188, 16, v222
	v_and_b32_e32 v189, 0xffff0000, v222
	v_lshlrev_b32_e32 v190, 16, v223
	v_and_b32_e32 v191, 0xffff0000, v223
	v_lshlrev_b32_e32 v246, 16, v224
	v_and_b32_e32 v247, 0xffff0000, v224
	v_lshlrev_b32_e32 v248, 16, v225
	v_and_b32_e32 v249, 0xffff0000, v225
	v_lshl_add_u64 v[148:149], v[180:181], 1, v[144:145]
	global_load_dwordx4 v[222:225], v[148:149], off
	v_pk_fma_f32 v[116:117], v[116:117], v[76:77], v[188:189]
	v_pk_fma_f32 v[118:119], v[118:119], v[78:79], v[190:191]
	v_pk_fma_f32 v[112:113], v[112:113], v[72:73], v[246:247]
	v_pk_fma_f32 v[114:115], v[114:115], v[74:75], v[248:249]
	v_cvt_pk_bf16_f32 v116, v116, v117
	v_cvt_pk_bf16_f32 v117, v118, v119
	v_cvt_pk_bf16_f32 v118, v112, v113
	v_cvt_pk_bf16_f32 v119, v114, v115
	global_store_dwordx4 v[192:193], v[116:119], off offset:256
	s_waitcnt vmcnt(12)
	v_lshlrev_b32_e32 v188, 16, v226
	v_and_b32_e32 v189, 0xffff0000, v226
	v_lshlrev_b32_e32 v190, 16, v227
	v_and_b32_e32 v191, 0xffff0000, v227
	v_lshlrev_b32_e32 v246, 16, v228
	v_and_b32_e32 v247, 0xffff0000, v228
	v_lshlrev_b32_e32 v248, 16, v229
	v_and_b32_e32 v249, 0xffff0000, v229
	global_load_dwordx4 v[226:229], v[148:149], off offset:256
	v_lshl_add_u64 v[150:151], v[172:173], 1, v[144:145]
	v_pk_fma_f32 v[108:109], v[108:109], v[92:93], v[188:189]
	v_pk_fma_f32 v[110:111], v[110:111], v[94:95], v[190:191]
	v_pk_fma_f32 v[104:105], v[104:105], v[84:85], v[246:247]
	v_pk_fma_f32 v[106:107], v[106:107], v[86:87], v[248:249]
	v_cvt_pk_bf16_f32 v108, v108, v109
	v_cvt_pk_bf16_f32 v109, v110, v111
	v_cvt_pk_bf16_f32 v110, v104, v105
	v_cvt_pk_bf16_f32 v111, v106, v107
	global_store_dwordx4 v[150:151], v[108:111], off
	s_waitcnt vmcnt(13)
	v_lshlrev_b32_e32 v188, 16, v230
	v_and_b32_e32 v189, 0xffff0000, v230
	v_lshlrev_b32_e32 v190, 16, v231
	v_and_b32_e32 v191, 0xffff0000, v231
	v_lshlrev_b32_e32 v246, 16, v232
	v_and_b32_e32 v247, 0xffff0000, v232
	v_lshlrev_b32_e32 v248, 16, v233
	v_and_b32_e32 v249, 0xffff0000, v233
	v_lshl_add_u64 v[148:149], v[182:183], 1, v[144:145]
	global_load_dwordx4 v[230:233], v[148:149], off
	v_pk_fma_f32 v[100:101], v[100:101], v[76:77], v[188:189]
	v_pk_fma_f32 v[102:103], v[102:103], v[78:79], v[190:191]
	v_pk_fma_f32 v[96:97], v[96:97], v[72:73], v[246:247]
	v_pk_fma_f32 v[98:99], v[98:99], v[74:75], v[248:249]
	v_cvt_pk_bf16_f32 v100, v100, v101
	v_cvt_pk_bf16_f32 v101, v102, v103
	v_cvt_pk_bf16_f32 v102, v96, v97
	v_cvt_pk_bf16_f32 v103, v98, v99
	global_store_dwordx4 v[150:151], v[100:103], off offset:256
	s_waitcnt vmcnt(14)
	v_lshlrev_b32_e32 v188, 16, v234
	v_and_b32_e32 v189, 0xffff0000, v234
	v_lshlrev_b32_e32 v190, 16, v235
	v_and_b32_e32 v191, 0xffff0000, v235
	v_lshlrev_b32_e32 v246, 16, v236
	v_and_b32_e32 v247, 0xffff0000, v236
	v_lshlrev_b32_e32 v248, 16, v237
	v_and_b32_e32 v249, 0xffff0000, v237
	global_load_dwordx4 v[234:237], v[148:149], off offset:256
	v_lshl_add_u64 v[192:193], v[174:175], 1, v[144:145]
	v_pk_fma_f32 v[88:89], v[88:89], v[92:93], v[188:189]
	v_pk_fma_f32 v[90:91], v[90:91], v[94:95], v[190:191]
	v_pk_fma_f32 v[80:81], v[80:81], v[84:85], v[246:247]
	v_pk_fma_f32 v[82:83], v[82:83], v[86:87], v[248:249]
	v_cvt_pk_bf16_f32 v88, v88, v89
	v_cvt_pk_bf16_f32 v89, v90, v91
	v_cvt_pk_bf16_f32 v90, v80, v81
	v_cvt_pk_bf16_f32 v91, v82, v83
	global_store_dwordx4 v[192:193], v[88:91], off
	s_waitcnt vmcnt(15)
	v_lshlrev_b32_e32 v188, 16, v238
	v_and_b32_e32 v189, 0xffff0000, v238
	v_lshlrev_b32_e32 v190, 16, v239
	v_and_b32_e32 v191, 0xffff0000, v239
	v_lshlrev_b32_e32 v246, 16, v240
	v_and_b32_e32 v247, 0xffff0000, v240
	v_lshlrev_b32_e32 v248, 16, v241
	v_and_b32_e32 v249, 0xffff0000, v241
	v_pk_fma_f32 v[68:69], v[68:69], v[76:77], v[188:189]
	v_pk_fma_f32 v[70:71], v[70:71], v[78:79], v[190:191]
	v_pk_fma_f32 v[64:65], v[64:65], v[72:73], v[246:247]
	v_pk_fma_f32 v[66:67], v[66:67], v[74:75], v[248:249]
	v_cvt_pk_bf16_f32 v68, v68, v69
	v_cvt_pk_bf16_f32 v69, v70, v71
	v_cvt_pk_bf16_f32 v70, v64, v65
	v_cvt_pk_bf16_f32 v71, v66, v67
	global_store_dwordx4 v[192:193], v[68:71], off offset:256
	s_waitcnt vmcnt(15)
	v_lshlrev_b32_e32 v188, 16, v242
	v_and_b32_e32 v189, 0xffff0000, v242
	v_lshlrev_b32_e32 v190, 16, v243
	v_and_b32_e32 v191, 0xffff0000, v243
	v_lshlrev_b32_e32 v246, 16, v244
	v_and_b32_e32 v247, 0xffff0000, v244
	v_lshlrev_b32_e32 v248, 16, v245
	v_and_b32_e32 v249, 0xffff0000, v245
	v_lshl_add_u64 v[150:151], v[176:177], 1, v[144:145]
	v_pk_fma_f32 v[60:61], v[60:61], v[92:93], v[188:189]
	v_pk_fma_f32 v[62:63], v[62:63], v[94:95], v[190:191]
	v_pk_fma_f32 v[56:57], v[56:57], v[84:85], v[246:247]
	v_pk_fma_f32 v[58:59], v[58:59], v[86:87], v[248:249]
	v_cvt_pk_bf16_f32 v60, v60, v61
	v_cvt_pk_bf16_f32 v61, v62, v63
	v_cvt_pk_bf16_f32 v62, v56, v57
	v_cvt_pk_bf16_f32 v63, v58, v59
	global_store_dwordx4 v[150:151], v[60:63], off
	s_waitcnt vmcnt(15)
	v_lshlrev_b32_e32 v188, 16, v210
	v_and_b32_e32 v189, 0xffff0000, v210
	v_lshlrev_b32_e32 v190, 16, v211
	v_and_b32_e32 v191, 0xffff0000, v211
	v_lshlrev_b32_e32 v246, 16, v212
	v_and_b32_e32 v247, 0xffff0000, v212
	v_lshlrev_b32_e32 v248, 16, v213
	v_and_b32_e32 v249, 0xffff0000, v213
	v_pk_fma_f32 v[52:53], v[52:53], v[76:77], v[188:189]
	v_pk_fma_f32 v[54:55], v[54:55], v[78:79], v[190:191]
	v_pk_fma_f32 v[48:49], v[48:49], v[72:73], v[246:247]
	v_pk_fma_f32 v[50:51], v[50:51], v[74:75], v[248:249]
	v_cvt_pk_bf16_f32 v52, v52, v53
	v_cvt_pk_bf16_f32 v53, v54, v55
	v_cvt_pk_bf16_f32 v54, v48, v49
	v_cvt_pk_bf16_f32 v55, v50, v51
	global_store_dwordx4 v[150:151], v[52:55], off offset:256
	s_waitcnt vmcnt(14)
	v_lshlrev_b32_e32 v188, 16, v214
	v_and_b32_e32 v189, 0xffff0000, v214
	v_lshlrev_b32_e32 v190, 16, v215
	v_and_b32_e32 v191, 0xffff0000, v215
	v_lshlrev_b32_e32 v246, 16, v216
	v_and_b32_e32 v247, 0xffff0000, v216
	v_lshlrev_b32_e32 v248, 16, v217
	v_and_b32_e32 v249, 0xffff0000, v217
	v_lshl_add_u64 v[192:193], v[178:179], 1, v[144:145]
	v_pk_fma_f32 v[44:45], v[44:45], v[92:93], v[188:189]
	v_pk_fma_f32 v[46:47], v[46:47], v[94:95], v[190:191]
	v_pk_fma_f32 v[40:41], v[40:41], v[84:85], v[246:247]
	v_pk_fma_f32 v[42:43], v[42:43], v[86:87], v[248:249]
	v_cvt_pk_bf16_f32 v44, v44, v45
	v_cvt_pk_bf16_f32 v45, v46, v47
	v_cvt_pk_bf16_f32 v46, v40, v41
	v_cvt_pk_bf16_f32 v47, v42, v43
	global_store_dwordx4 v[192:193], v[44:47], off
	s_waitcnt vmcnt(13)
	v_lshlrev_b32_e32 v188, 16, v218
	v_and_b32_e32 v189, 0xffff0000, v218
	v_lshlrev_b32_e32 v190, 16, v219
	v_and_b32_e32 v191, 0xffff0000, v219
	v_lshlrev_b32_e32 v246, 16, v220
	v_and_b32_e32 v247, 0xffff0000, v220
	v_lshlrev_b32_e32 v248, 16, v221
	v_and_b32_e32 v249, 0xffff0000, v221
	v_pk_fma_f32 v[36:37], v[36:37], v[76:77], v[188:189]
	v_pk_fma_f32 v[38:39], v[38:39], v[78:79], v[190:191]
	v_pk_fma_f32 v[32:33], v[32:33], v[72:73], v[246:247]
	v_pk_fma_f32 v[34:35], v[34:35], v[74:75], v[248:249]
	v_cvt_pk_bf16_f32 v36, v36, v37
	v_cvt_pk_bf16_f32 v37, v38, v39
	v_cvt_pk_bf16_f32 v38, v32, v33
	v_cvt_pk_bf16_f32 v39, v34, v35
	global_store_dwordx4 v[192:193], v[36:39], off offset:256
	s_waitcnt vmcnt(12)
	v_lshlrev_b32_e32 v188, 16, v222
	v_and_b32_e32 v189, 0xffff0000, v222
	v_lshlrev_b32_e32 v190, 16, v223
	v_and_b32_e32 v191, 0xffff0000, v223
	v_lshlrev_b32_e32 v246, 16, v224
	v_and_b32_e32 v247, 0xffff0000, v224
	v_lshlrev_b32_e32 v248, 16, v225
	v_and_b32_e32 v249, 0xffff0000, v225
	v_lshl_add_u64 v[150:151], v[180:181], 1, v[144:145]
	v_pk_fma_f32 v[28:29], v[28:29], v[92:93], v[188:189]
	v_pk_fma_f32 v[30:31], v[30:31], v[94:95], v[190:191]
	v_pk_fma_f32 v[24:25], v[24:25], v[84:85], v[246:247]
	v_pk_fma_f32 v[26:27], v[26:27], v[86:87], v[248:249]
	v_cvt_pk_bf16_f32 v28, v28, v29
	v_cvt_pk_bf16_f32 v29, v30, v31
	v_cvt_pk_bf16_f32 v30, v24, v25
	v_cvt_pk_bf16_f32 v31, v26, v27
	global_store_dwordx4 v[150:151], v[28:31], off
	s_waitcnt vmcnt(11)
	v_lshlrev_b32_e32 v188, 16, v226
	v_and_b32_e32 v189, 0xffff0000, v226
	v_lshlrev_b32_e32 v190, 16, v227
	v_and_b32_e32 v191, 0xffff0000, v227
	v_lshlrev_b32_e32 v246, 16, v228
	v_and_b32_e32 v247, 0xffff0000, v228
	v_lshlrev_b32_e32 v248, 16, v229
	v_and_b32_e32 v249, 0xffff0000, v229
	v_pk_fma_f32 v[20:21], v[20:21], v[76:77], v[188:189]
	v_pk_fma_f32 v[22:23], v[22:23], v[78:79], v[190:191]
	v_pk_fma_f32 v[16:17], v[16:17], v[72:73], v[246:247]
	v_pk_fma_f32 v[18:19], v[18:19], v[74:75], v[248:249]
	v_cvt_pk_bf16_f32 v20, v20, v21
	v_cvt_pk_bf16_f32 v21, v22, v23
	v_cvt_pk_bf16_f32 v22, v16, v17
	v_cvt_pk_bf16_f32 v23, v18, v19
	global_store_dwordx4 v[150:151], v[20:23], off offset:256
	s_waitcnt vmcnt(10)
	v_lshlrev_b32_e32 v188, 16, v230
	v_and_b32_e32 v189, 0xffff0000, v230
	v_lshlrev_b32_e32 v190, 16, v231
	v_and_b32_e32 v191, 0xffff0000, v231
	v_lshlrev_b32_e32 v246, 16, v232
	v_and_b32_e32 v247, 0xffff0000, v232
	v_lshlrev_b32_e32 v248, 16, v233
	v_and_b32_e32 v249, 0xffff0000, v233
	v_lshl_add_u64 v[192:193], v[182:183], 1, v[144:145]
	v_pk_fma_f32 v[12:13], v[12:13], v[92:93], v[188:189]
	v_pk_fma_f32 v[14:15], v[14:15], v[94:95], v[190:191]
	v_pk_fma_f32 v[8:9], v[8:9], v[84:85], v[246:247]
	v_pk_fma_f32 v[10:11], v[10:11], v[86:87], v[248:249]
	v_cvt_pk_bf16_f32 v12, v12, v13
	v_cvt_pk_bf16_f32 v13, v14, v15
	v_cvt_pk_bf16_f32 v14, v8, v9
	v_cvt_pk_bf16_f32 v15, v10, v11
	global_store_dwordx4 v[192:193], v[12:15], off
	s_waitcnt vmcnt(9)
	v_lshlrev_b32_e32 v188, 16, v234
	v_and_b32_e32 v189, 0xffff0000, v234
	v_lshlrev_b32_e32 v190, 16, v235
	v_and_b32_e32 v191, 0xffff0000, v235
	v_lshlrev_b32_e32 v246, 16, v236
	v_and_b32_e32 v247, 0xffff0000, v236
	v_lshlrev_b32_e32 v248, 16, v237
	v_and_b32_e32 v249, 0xffff0000, v237
	v_pk_fma_f32 v[4:5], v[4:5], v[76:77], v[188:189]
	v_pk_fma_f32 v[6:7], v[6:7], v[78:79], v[190:191]
	v_pk_fma_f32 v[0:1], v[0:1], v[72:73], v[246:247]
	v_pk_fma_f32 v[2:3], v[2:3], v[74:75], v[248:249]
	v_cvt_pk_bf16_f32 v4, v4, v5
	v_cvt_pk_bf16_f32 v5, v6, v7
	v_cvt_pk_bf16_f32 v6, v0, v1
	v_cvt_pk_bf16_f32 v7, v2, v3
	global_store_dwordx4 v[192:193], v[4:7], off offset:256
	s_branch .Lwo_epi_done

.LBB0_630:
	s_waitcnt vmcnt(0)
	s_cmpk_gt_u32 s15, 0xff
	s_cbranch_scc1 .LBB0_632
.LBB0_632:
	v_readlane_b32 s34, v253, 45
	v_readlane_b32 s35, v253, 46
	s_mov_b32 s80, s92
	s_barrier

.LBB0_772:
	s_ashr_i32 s35, s34, 31
	v_cmp_lt_i64_e32 vcc, s[42:43], v[156:157]
	s_lshl_b64 s[42:43], s[34:35], 20
	s_add_u32 s42, s15, s42
	s_addc_u32 s43, s30, s43
	s_and_b64 s[44:45], vcc, exec
	s_cselect_b32 s35, s43, s21
	s_cselect_b32 s56, s42, s20
	s_ashr_i32 s25, s24, 31
	s_lshl_b64 s[44:45], s[24:25], 20
	s_add_u32 s44, s48, s44
	s_addc_u32 s45, s49, s45
	s_and_b64 s[46:47], vcc, exec
	s_cselect_b32 s25, s45, s23
	s_cselect_b32 s57, s44, s22
	s_add_u32 s20, s20, 0x80080
	s_addc_u32 s21, s21, 0
	s_add_u32 s58, s22, 0x100
	v_mov_b32_e32 v0, 0
	s_addc_u32 s59, s23, 0
	s_mov_b32 s60, -2
	v_mov_b32_e32 v1, v0
	v_mov_b32_e32 v2, v0
	v_mov_b32_e32 v3, v0
	v_mov_b32_e32 v4, v0
	v_mov_b32_e32 v5, v0
	v_mov_b32_e32 v6, v0
	v_mov_b32_e32 v7, v0
	v_mov_b32_e32 v16, v0
	v_mov_b32_e32 v17, v0
	v_mov_b32_e32 v18, v0
	v_mov_b32_e32 v19, v0
	v_mov_b32_e32 v20, v0
	v_mov_b32_e32 v21, v0
	v_mov_b32_e32 v22, v0
	v_mov_b32_e32 v23, v0
	v_mov_b32_e32 v32, v0
	v_mov_b32_e32 v33, v0
	v_mov_b32_e32 v34, v0
	v_mov_b32_e32 v35, v0
	v_mov_b32_e32 v36, v0
	v_mov_b32_e32 v37, v0
	v_mov_b32_e32 v38, v0
	v_mov_b32_e32 v39, v0
	v_mov_b32_e32 v48, v0
	v_mov_b32_e32 v49, v0
	v_mov_b32_e32 v50, v0
	v_mov_b32_e32 v51, v0
	v_mov_b32_e32 v52, v0
	v_mov_b32_e32 v53, v0
	v_mov_b32_e32 v54, v0
	v_mov_b32_e32 v55, v0
	v_mov_b32_e32 v8, v0
	v_mov_b32_e32 v9, v0
	v_mov_b32_e32 v10, v0
	v_mov_b32_e32 v11, v0
	v_mov_b32_e32 v12, v0
	v_mov_b32_e32 v13, v0
	v_mov_b32_e32 v14, v0
	v_mov_b32_e32 v15, v0
	v_mov_b32_e32 v24, v0
	v_mov_b32_e32 v25, v0
	v_mov_b32_e32 v26, v0
	v_mov_b32_e32 v27, v0
	v_mov_b32_e32 v28, v0
	v_mov_b32_e32 v29, v0
	v_mov_b32_e32 v30, v0
	v_mov_b32_e32 v31, v0
	v_mov_b32_e32 v40, v0
	v_mov_b32_e32 v41, v0
	v_mov_b32_e32 v42, v0
	v_mov_b32_e32 v43, v0
	v_mov_b32_e32 v44, v0
	v_mov_b32_e32 v45, v0
	v_mov_b32_e32 v46, v0
	v_mov_b32_e32 v47, v0
	v_mov_b32_e32 v56, v0
	v_mov_b32_e32 v57, v0
	v_mov_b32_e32 v58, v0
	v_mov_b32_e32 v59, v0
	v_mov_b32_e32 v60, v0
	v_mov_b32_e32 v61, v0
	v_mov_b32_e32 v62, v0
	v_mov_b32_e32 v63, v0
	v_mov_b32_e32 v64, v0
	v_mov_b32_e32 v65, v0
	v_mov_b32_e32 v66, v0
	v_mov_b32_e32 v67, v0
	v_mov_b32_e32 v68, v0
	v_mov_b32_e32 v69, v0
	v_mov_b32_e32 v70, v0
	v_mov_b32_e32 v71, v0
	v_mov_b32_e32 v80, v0
	v_mov_b32_e32 v81, v0
	v_mov_b32_e32 v82, v0
	v_mov_b32_e32 v83, v0
	v_mov_b32_e32 v84, v0
	v_mov_b32_e32 v85, v0
	v_mov_b32_e32 v86, v0
	v_mov_b32_e32 v87, v0
	v_mov_b32_e32 v96, v0
	v_mov_b32_e32 v97, v0
	v_mov_b32_e32 v98, v0
	v_mov_b32_e32 v99, v0
	v_mov_b32_e32 v100, v0
	v_mov_b32_e32 v101, v0
	v_mov_b32_e32 v102, v0
	v_mov_b32_e32 v103, v0
	v_mov_b32_e32 v112, v0
	v_mov_b32_e32 v113, v0
	v_mov_b32_e32 v114, v0
	v_mov_b32_e32 v115, v0
	v_mov_b32_e32 v116, v0
	v_mov_b32_e32 v117, v0
	v_mov_b32_e32 v118, v0
	v_mov_b32_e32 v119, v0
	v_mov_b32_e32 v72, v0
	v_mov_b32_e32 v73, v0
	v_mov_b32_e32 v74, v0
	v_mov_b32_e32 v75, v0
	v_mov_b32_e32 v76, v0
	v_mov_b32_e32 v77, v0
	v_mov_b32_e32 v78, v0
	v_mov_b32_e32 v79, v0
	v_mov_b32_e32 v88, v0
	v_mov_b32_e32 v89, v0
	v_mov_b32_e32 v90, v0
	v_mov_b32_e32 v91, v0
	v_mov_b32_e32 v92, v0
	v_mov_b32_e32 v93, v0
	v_mov_b32_e32 v94, v0
	v_mov_b32_e32 v95, v0
	v_mov_b32_e32 v104, v0
	v_mov_b32_e32 v105, v0
	v_mov_b32_e32 v106, v0
	v_mov_b32_e32 v107, v0
	v_mov_b32_e32 v108, v0
	v_mov_b32_e32 v109, v0
	v_mov_b32_e32 v110, v0
	v_mov_b32_e32 v111, v0
	v_mov_b32_e32 v120, v0
	v_mov_b32_e32 v121, v0
	v_mov_b32_e32 v122, v0
	v_mov_b32_e32 v123, v0
	v_mov_b32_e32 v124, v0
	v_mov_b32_e32 v125, v0
	v_mov_b32_e32 v126, v0
	v_mov_b32_e32 v127, v0
	s_cmpk_lt_u32 s14, 0x100
	s_cbranch_scc1 .Lal_e1_m
	s_cmp_lt_u32 s55, 2
	s_cbranch_scc1 .Lal_e1_m
	s_barrier
.Lal_e1_m:
	v_add_u32_e32 v230, 0x10000, v141
	v_add_u32_e32 v231, 0x14000, v141
	v_add_u32_e32 v232, 0x18000, v141
	v_add_u32_e32 v233, 0x1c000, v141
	s_add_u32 s22, s20, 0xfff80080
	s_addc_u32 s23, s21, -1
	s_add_i32 s61, 0, 0x10000
	s_cmp_eq_u32 s60, 28
	s_cselect_b32 s47, s35, s23
	s_cselect_b32 s46, s56, s22
	s_cselect_b32 s23, s25, s59
	s_cselect_b32 s22, s57, s58
	s_add_i32 m0, s5, 0xc000
.LBB0_773:
	ds_read_b128 v[144:147], v230
	ds_read_b128 v[148:151], v230 offset:1024
	ds_read_b128 v[162:165], v230 offset:2048
	ds_read_b128 v[166:169], v230 offset:3072
	ds_read_b128 v[170:173], v143
	ds_read_b128 v[174:177], v143 offset:1024
	ds_read_b128 v[178:181], v143 offset:2048
	ds_read_b128 v[182:185], v143 offset:3072
	ds_read_b128 v[186:189], v143 offset:4096
	ds_read_b128 v[190:193], v143 offset:5120
	ds_read_b128 v[206:209], v143 offset:6144
	ds_read_b128 v[210:213], v143 offset:7168
	global_load_lds_dwordx4 v134, s[20:21]
	s_add_i32 m0, s5, 0xe000
	s_nop 0
	global_load_lds_dwordx4 v136, s[20:21]
	s_waitcnt lgkmcnt(8)
	s_barrier
	s_waitcnt lgkmcnt(0)
	v_mfma_f32_16x16x32_bf16 v[124:127], v[144:147], v[170:173], v[124:127]
	v_mfma_f32_16x16x32_bf16 v[120:123], v[162:165], v[170:173], v[120:123]
	v_mfma_f32_16x16x32_bf16 v[108:111], v[144:147], v[178:181], v[108:111]
	v_mfma_f32_16x16x32_bf16 v[104:107], v[162:165], v[178:181], v[104:107]
	v_mfma_f32_16x16x32_bf16 v[92:95], v[144:147], v[186:189], v[92:95]
	v_mfma_f32_16x16x32_bf16 v[88:91], v[162:165], v[186:189], v[88:91]
	v_mfma_f32_16x16x32_bf16 v[76:79], v[144:147], v[206:209], v[76:79]
	v_mfma_f32_16x16x32_bf16 v[72:75], v[162:165], v[206:209], v[72:75]
	v_mfma_f32_16x16x32_bf16 v[124:127], v[148:151], v[174:177], v[124:127]
	v_mfma_f32_16x16x32_bf16 v[120:123], v[166:169], v[174:177], v[120:123]
	v_mfma_f32_16x16x32_bf16 v[108:111], v[148:151], v[182:185], v[108:111]
	v_mfma_f32_16x16x32_bf16 v[104:107], v[166:169], v[182:185], v[104:107]
	v_mfma_f32_16x16x32_bf16 v[92:95], v[148:151], v[190:193], v[92:95]
	v_mfma_f32_16x16x32_bf16 v[88:91], v[166:169], v[190:193], v[88:91]
	v_mfma_f32_16x16x32_bf16 v[76:79], v[148:151], v[210:213], v[76:79]
	v_mfma_f32_16x16x32_bf16 v[72:75], v[166:169], v[210:213], v[72:75]
	s_barrier
	s_add_i32 s68, 0, 0x14000
	s_add_i32 s61, s61, s4
	ds_read_b128 v[214:217], v231
	ds_read_b128 v[218:221], v231 offset:1024
	ds_read_b128 v[222:225], v231 offset:2048
	ds_read_b128 v[226:229], v231 offset:3072
	s_mov_b32 m0, s61
	s_nop 0
	global_load_lds_dwordx4 v152, s[22:23]
	s_add_i32 m0, s61, 0x2000
	s_nop 0
	global_load_lds_dwordx4 v132, s[22:23]
	s_barrier
	s_waitcnt lgkmcnt(0)
	v_mfma_f32_16x16x32_bf16 v[116:119], v[214:217], v[170:173], v[116:119]
	v_mfma_f32_16x16x32_bf16 v[112:115], v[222:225], v[170:173], v[112:115]
	v_mfma_f32_16x16x32_bf16 v[100:103], v[214:217], v[178:181], v[100:103]
	v_mfma_f32_16x16x32_bf16 v[96:99], v[222:225], v[178:181], v[96:99]
	v_mfma_f32_16x16x32_bf16 v[84:87], v[214:217], v[186:189], v[84:87]
	v_mfma_f32_16x16x32_bf16 v[80:83], v[222:225], v[186:189], v[80:83]
	v_mfma_f32_16x16x32_bf16 v[68:71], v[214:217], v[206:209], v[68:71]
	v_mfma_f32_16x16x32_bf16 v[64:67], v[222:225], v[206:209], v[64:67]
	v_mfma_f32_16x16x32_bf16 v[116:119], v[218:221], v[174:177], v[116:119]
	v_mfma_f32_16x16x32_bf16 v[112:115], v[226:229], v[174:177], v[112:115]
	v_mfma_f32_16x16x32_bf16 v[100:103], v[218:221], v[182:185], v[100:103]
	v_mfma_f32_16x16x32_bf16 v[96:99], v[226:229], v[182:185], v[96:99]
	v_mfma_f32_16x16x32_bf16 v[84:87], v[218:221], v[190:193], v[84:87]
	v_mfma_f32_16x16x32_bf16 v[80:83], v[226:229], v[190:193], v[80:83]
	v_mfma_f32_16x16x32_bf16 v[68:71], v[218:221], v[210:213], v[68:71]
	v_mfma_f32_16x16x32_bf16 v[64:67], v[226:229], v[210:213], v[64:67]
	s_barrier
	s_mov_b32 m0, s5
	s_add_u32 s98, s46, 0x80
	s_addc_u32 s99, s47, 0
	ds_read_b128 v[170:173], v143 offset:16384
	ds_read_b128 v[174:177], v143 offset:17408
	ds_read_b128 v[178:181], v143 offset:18432
	ds_read_b128 v[182:185], v143 offset:19456
	ds_read_b128 v[186:189], v143 offset:20480
	ds_read_b128 v[190:193], v143 offset:21504
	ds_read_b128 v[206:209], v143 offset:22528
	ds_read_b128 v[210:213], v143 offset:23552
	global_load_lds_dwordx4 v128, s[46:47]
	s_mov_b32 m0, s50
	s_nop 0
	global_load_lds_dwordx4 v130, s[46:47]
	s_barrier
	s_waitcnt lgkmcnt(0)
	v_mfma_f32_16x16x32_bf16 v[60:63], v[144:147], v[170:173], v[60:63]
	v_mfma_f32_16x16x32_bf16 v[56:59], v[162:165], v[170:173], v[56:59]
	v_mfma_f32_16x16x32_bf16 v[44:47], v[144:147], v[178:181], v[44:47]
	v_mfma_f32_16x16x32_bf16 v[40:43], v[162:165], v[178:181], v[40:43]
	v_mfma_f32_16x16x32_bf16 v[28:31], v[144:147], v[186:189], v[28:31]
	v_mfma_f32_16x16x32_bf16 v[24:27], v[162:165], v[186:189], v[24:27]
	v_mfma_f32_16x16x32_bf16 v[12:15], v[144:147], v[206:209], v[12:15]
	v_mfma_f32_16x16x32_bf16 v[8:11], v[162:165], v[206:209], v[8:11]
	v_mfma_f32_16x16x32_bf16 v[60:63], v[148:151], v[174:177], v[60:63]
	v_mfma_f32_16x16x32_bf16 v[56:59], v[166:169], v[174:177], v[56:59]
	v_mfma_f32_16x16x32_bf16 v[44:47], v[148:151], v[182:185], v[44:47]
	v_mfma_f32_16x16x32_bf16 v[40:43], v[166:169], v[182:185], v[40:43]
	v_mfma_f32_16x16x32_bf16 v[28:31], v[148:151], v[190:193], v[28:31]
	v_mfma_f32_16x16x32_bf16 v[24:27], v[166:169], v[190:193], v[24:27]
	v_mfma_f32_16x16x32_bf16 v[12:15], v[148:151], v[210:213], v[12:15]
	v_mfma_f32_16x16x32_bf16 v[8:11], v[166:169], v[210:213], v[8:11]
	s_barrier
	s_add_u32 s62, s22, 0x80000
	s_addc_u32 s63, s23, 0
	s_add_i32 s61, s68, s4
	s_mov_b32 m0, s61
	s_nop 0
	global_load_lds_dwordx4 v152, s[62:63]
	s_add_i32 m0, s61, 0x2000
	s_nop 0
	global_load_lds_dwordx4 v132, s[62:63]
	s_add_i32 s61, 0, 0x18000
	s_add_u32 s46, s46, 0x80000
	s_addc_u32 s47, s47, 0
	s_mov_b32 m0, s51
	s_waitcnt vmcnt(6)
	s_barrier
	v_mfma_f32_16x16x32_bf16 v[52:55], v[214:217], v[170:173], v[52:55]
	v_mfma_f32_16x16x32_bf16 v[48:51], v[222:225], v[170:173], v[48:51]
	v_mfma_f32_16x16x32_bf16 v[36:39], v[214:217], v[178:181], v[36:39]
	v_mfma_f32_16x16x32_bf16 v[32:35], v[222:225], v[178:181], v[32:35]
	v_mfma_f32_16x16x32_bf16 v[20:23], v[214:217], v[186:189], v[20:23]
	v_mfma_f32_16x16x32_bf16 v[16:19], v[222:225], v[186:189], v[16:19]
	v_mfma_f32_16x16x32_bf16 v[4:7], v[214:217], v[206:209], v[4:7]
	v_mfma_f32_16x16x32_bf16 v[0:3], v[222:225], v[206:209], v[0:3]
	v_mfma_f32_16x16x32_bf16 v[52:55], v[218:221], v[174:177], v[52:55]
	v_mfma_f32_16x16x32_bf16 v[48:51], v[226:229], v[174:177], v[48:51]
	v_mfma_f32_16x16x32_bf16 v[36:39], v[218:221], v[182:185], v[36:39]
	v_mfma_f32_16x16x32_bf16 v[32:35], v[226:229], v[182:185], v[32:35]
	v_mfma_f32_16x16x32_bf16 v[20:23], v[218:221], v[190:193], v[20:23]
	v_mfma_f32_16x16x32_bf16 v[16:19], v[226:229], v[190:193], v[16:19]
	v_mfma_f32_16x16x32_bf16 v[4:7], v[218:221], v[210:213], v[4:7]
	v_mfma_f32_16x16x32_bf16 v[0:3], v[226:229], v[210:213], v[0:3]
	s_barrier
	ds_read_b128 v[144:147], v232
	ds_read_b128 v[148:151], v232 offset:1024
	ds_read_b128 v[162:165], v232 offset:2048
	ds_read_b128 v[166:169], v232 offset:3072
	ds_read_b128 v[170:173], v143 offset:32768
	ds_read_b128 v[174:177], v143 offset:33792
	ds_read_b128 v[178:181], v143 offset:34816
	ds_read_b128 v[182:185], v143 offset:35840
	ds_read_b128 v[186:189], v143 offset:36864
	ds_read_b128 v[190:193], v143 offset:37888
	ds_read_b128 v[206:209], v143 offset:38912
	ds_read_b128 v[210:213], v143 offset:39936
	global_load_lds_dwordx4 v128, s[46:47]
	s_mov_b32 m0, s52
	s_nop 0
	global_load_lds_dwordx4 v130, s[46:47]
	s_waitcnt lgkmcnt(8)
	s_barrier
	s_waitcnt lgkmcnt(0)
	v_mfma_f32_16x16x32_bf16 v[124:127], v[144:147], v[170:173], v[124:127]
	v_mfma_f32_16x16x32_bf16 v[120:123], v[162:165], v[170:173], v[120:123]
	v_mfma_f32_16x16x32_bf16 v[108:111], v[144:147], v[178:181], v[108:111]
	v_mfma_f32_16x16x32_bf16 v[104:107], v[162:165], v[178:181], v[104:107]
	v_mfma_f32_16x16x32_bf16 v[92:95], v[144:147], v[186:189], v[92:95]
	v_mfma_f32_16x16x32_bf16 v[88:91], v[162:165], v[186:189], v[88:91]
	v_mfma_f32_16x16x32_bf16 v[76:79], v[144:147], v[206:209], v[76:79]
	v_mfma_f32_16x16x32_bf16 v[72:75], v[162:165], v[206:209], v[72:75]
	v_mfma_f32_16x16x32_bf16 v[124:127], v[148:151], v[174:177], v[124:127]
	v_mfma_f32_16x16x32_bf16 v[120:123], v[166:169], v[174:177], v[120:123]
	v_mfma_f32_16x16x32_bf16 v[108:111], v[148:151], v[182:185], v[108:111]
	v_mfma_f32_16x16x32_bf16 v[104:107], v[166:169], v[182:185], v[104:107]
	v_mfma_f32_16x16x32_bf16 v[92:95], v[148:151], v[190:193], v[92:95]
	v_mfma_f32_16x16x32_bf16 v[88:91], v[166:169], v[190:193], v[88:91]
	v_mfma_f32_16x16x32_bf16 v[76:79], v[148:151], v[210:213], v[76:79]
	v_mfma_f32_16x16x32_bf16 v[72:75], v[166:169], v[210:213], v[72:75]
	s_barrier
	s_add_i32 s46, 0, 0x1c000
	s_add_i32 s47, s61, s4
	s_add_u32 s100, s22, 0x80
	s_addc_u32 s101, s23, 0
	s_mov_b32 m0, s47
	ds_read_b128 v[214:217], v233
	ds_read_b128 v[218:221], v233 offset:1024
	ds_read_b128 v[222:225], v233 offset:2048
	ds_read_b128 v[226:229], v233 offset:3072
	global_load_lds_dwordx4 v152, s[100:101]
	s_add_i32 m0, s47, 0x2000
	s_nop 0
	global_load_lds_dwordx4 v132, s[100:101]
	s_barrier
	s_waitcnt lgkmcnt(0)
	v_mfma_f32_16x16x32_bf16 v[116:119], v[214:217], v[170:173], v[116:119]
	v_mfma_f32_16x16x32_bf16 v[112:115], v[222:225], v[170:173], v[112:115]
	v_mfma_f32_16x16x32_bf16 v[100:103], v[214:217], v[178:181], v[100:103]
	v_mfma_f32_16x16x32_bf16 v[96:99], v[222:225], v[178:181], v[96:99]
	v_mfma_f32_16x16x32_bf16 v[84:87], v[214:217], v[186:189], v[84:87]
	v_mfma_f32_16x16x32_bf16 v[80:83], v[222:225], v[186:189], v[80:83]
	v_mfma_f32_16x16x32_bf16 v[68:71], v[214:217], v[206:209], v[68:71]
	v_mfma_f32_16x16x32_bf16 v[64:67], v[222:225], v[206:209], v[64:67]
	v_mfma_f32_16x16x32_bf16 v[116:119], v[218:221], v[174:177], v[116:119]
	v_mfma_f32_16x16x32_bf16 v[112:115], v[226:229], v[174:177], v[112:115]
	v_mfma_f32_16x16x32_bf16 v[100:103], v[218:221], v[182:185], v[100:103]
	v_mfma_f32_16x16x32_bf16 v[96:99], v[226:229], v[182:185], v[96:99]
	v_mfma_f32_16x16x32_bf16 v[84:87], v[218:221], v[190:193], v[84:87]
	v_mfma_f32_16x16x32_bf16 v[80:83], v[226:229], v[190:193], v[80:83]
	v_mfma_f32_16x16x32_bf16 v[68:71], v[218:221], v[210:213], v[68:71]
	v_mfma_f32_16x16x32_bf16 v[64:67], v[226:229], v[210:213], v[64:67]
	s_barrier
	s_mov_b32 m0, s53
	ds_read_b128 v[170:173], v143 offset:49152
	ds_read_b128 v[174:177], v143 offset:50176
	ds_read_b128 v[178:181], v143 offset:51200
	ds_read_b128 v[182:185], v143 offset:52224
	ds_read_b128 v[186:189], v143 offset:53248
	ds_read_b128 v[190:193], v143 offset:54272
	ds_read_b128 v[206:209], v143 offset:55296
	ds_read_b128 v[210:213], v143 offset:56320
	global_load_lds_dwordx4 v128, s[98:99]
	s_mov_b32 m0, s54
	s_nop 0
	global_load_lds_dwordx4 v130, s[98:99]
	s_barrier
	s_waitcnt lgkmcnt(0)
	v_mfma_f32_16x16x32_bf16 v[60:63], v[144:147], v[170:173], v[60:63]
	v_mfma_f32_16x16x32_bf16 v[56:59], v[162:165], v[170:173], v[56:59]
	v_mfma_f32_16x16x32_bf16 v[44:47], v[144:147], v[178:181], v[44:47]
	v_mfma_f32_16x16x32_bf16 v[40:43], v[162:165], v[178:181], v[40:43]
	v_mfma_f32_16x16x32_bf16 v[28:31], v[144:147], v[186:189], v[28:31]
	v_mfma_f32_16x16x32_bf16 v[24:27], v[162:165], v[186:189], v[24:27]
	v_mfma_f32_16x16x32_bf16 v[12:15], v[144:147], v[206:209], v[12:15]
	v_mfma_f32_16x16x32_bf16 v[8:11], v[162:165], v[206:209], v[8:11]
	v_mfma_f32_16x16x32_bf16 v[60:63], v[148:151], v[174:177], v[60:63]
	v_mfma_f32_16x16x32_bf16 v[56:59], v[166:169], v[174:177], v[56:59]
	v_mfma_f32_16x16x32_bf16 v[44:47], v[148:151], v[182:185], v[44:47]
	v_mfma_f32_16x16x32_bf16 v[40:43], v[166:169], v[182:185], v[40:43]
	v_mfma_f32_16x16x32_bf16 v[28:31], v[148:151], v[190:193], v[28:31]
	v_mfma_f32_16x16x32_bf16 v[24:27], v[166:169], v[190:193], v[24:27]
	v_mfma_f32_16x16x32_bf16 v[12:15], v[148:151], v[210:213], v[12:15]
	v_mfma_f32_16x16x32_bf16 v[8:11], v[166:169], v[210:213], v[8:11]
	s_barrier
	s_add_u32 s22, s22, 0x80080
	s_addc_u32 s23, s23, 0
	s_add_i32 s46, s46, s4
	s_mov_b32 m0, s46
	s_nop 0
	global_load_lds_dwordx4 v152, s[22:23]
	s_add_i32 m0, s46, 0x2000
	s_nop 0
	global_load_lds_dwordx4 v132, s[22:23]
	s_add_i32 s60, s60, 2
	s_add_u32 s20, s20, 0x100
	s_addc_u32 s21, s21, 0
	s_add_u32 s58, s58, 0x100
	s_addc_u32 s59, s59, 0
	s_add_u32 s22, s20, 0xfff80080
	s_addc_u32 s23, s21, -1
	s_add_i32 s61, 0, 0x10000
	s_cmp_eq_u32 s60, 28
	s_cselect_b32 s47, s35, s23
	s_cselect_b32 s46, s56, s22
	s_cselect_b32 s23, s25, s59
	s_cselect_b32 s22, s57, s58
	s_add_i32 m0, s5, 0xc000
	s_cmp_gt_u32 s60, 29
	s_waitcnt vmcnt(6)
	s_barrier
	v_mfma_f32_16x16x32_bf16 v[52:55], v[214:217], v[170:173], v[52:55]
	v_mfma_f32_16x16x32_bf16 v[48:51], v[222:225], v[170:173], v[48:51]
	v_mfma_f32_16x16x32_bf16 v[36:39], v[214:217], v[178:181], v[36:39]
	v_mfma_f32_16x16x32_bf16 v[32:35], v[222:225], v[178:181], v[32:35]
	v_mfma_f32_16x16x32_bf16 v[20:23], v[214:217], v[186:189], v[20:23]
	v_mfma_f32_16x16x32_bf16 v[16:19], v[222:225], v[186:189], v[16:19]
	v_mfma_f32_16x16x32_bf16 v[4:7], v[214:217], v[206:209], v[4:7]
	v_mfma_f32_16x16x32_bf16 v[0:3], v[222:225], v[206:209], v[0:3]
	v_mfma_f32_16x16x32_bf16 v[52:55], v[218:221], v[174:177], v[52:55]
	v_mfma_f32_16x16x32_bf16 v[48:51], v[226:229], v[174:177], v[48:51]
	v_mfma_f32_16x16x32_bf16 v[36:39], v[218:221], v[182:185], v[36:39]
	v_mfma_f32_16x16x32_bf16 v[32:35], v[226:229], v[182:185], v[32:35]
	v_mfma_f32_16x16x32_bf16 v[20:23], v[218:221], v[190:193], v[20:23]
	v_mfma_f32_16x16x32_bf16 v[16:19], v[226:229], v[190:193], v[16:19]
	v_mfma_f32_16x16x32_bf16 v[4:7], v[218:221], v[210:213], v[4:7]
	v_mfma_f32_16x16x32_bf16 v[0:3], v[226:229], v[210:213], v[0:3]
	s_barrier
	s_cbranch_scc0 .LBB0_773
	s_cmpk_gt_u32 s14, 0xff
	s_cbranch_scc1 .Lal_e0_m
	s_barrier
.Lal_e0_m:
	v_lshl_add_u32 v144, s7, 8, v140
	v_max_f32_e32 v120, v120, v120
	v_ashrrev_i32_e32 v145, 31, v144
	v_max_f32_e32 v120, 0, v120
	v_max_f32_e32 v121, v121, v121
	v_max_f32_e32 v122, v122, v122
	v_lshl_or_b32 v138, s6, 8, v142
	v_lshlrev_b64 v[146:147], 14, v[144:145]
	v_mul_f32_e32 v145, v120, v120
	v_max_f32_e32 v120, v125, v125
	v_max_f32_e32 v121, 0, v121
	v_max_f32_e32 v122, 0, v122
	v_ashrrev_i32_e32 v139, 31, v138
	v_max_f32_e32 v124, v124, v124
	v_max_f32_e32 v120, 0, v120
	v_mul_f32_e32 v125, v121, v121
	v_max_f32_e32 v121, v126, v126
	v_mul_f32_e32 v126, v122, v122
	v_max_f32_e32 v122, v127, v127
	v_max_f32_e32 v123, v123, v123
	v_lshl_add_u64 v[146:147], s[16:17], 0, v[146:147]
	v_lshlrev_b64 v[148:149], 1, v[138:139]
	v_max_f32_e32 v124, 0, v124
	v_mul_f32_e32 v120, v120, v120
	v_max_f32_e32 v121, 0, v121
	v_max_f32_e32 v122, 0, v122
	v_max_f32_e32 v123, 0, v123
	v_max_f32_e32 v112, v112, v112
	v_lshl_add_u64 v[138:139], v[146:147], 0, v[148:149]
	v_mul_f32_e32 v124, v124, v124
	v_mul_f32_e32 v121, v121, v121
	v_mul_f32_e32 v122, v122, v122
	v_mul_f32_e32 v123, v123, v123
	v_cvt_pk_bf16_f32 v120, v124, v120
	v_max_f32_e32 v112, 0, v112
	v_max_f32_e32 v113, v113, v113
	v_max_f32_e32 v114, v114, v114
	v_cvt_pk_bf16_f32 v121, v121, v122
	v_cvt_pk_bf16_f32 v122, v145, v125
	v_cvt_pk_bf16_f32 v123, v126, v123
	global_store_dwordx4 v[138:139], v[120:123], off
	v_max_f32_e32 v113, 0, v113
	v_max_f32_e32 v114, 0, v114
	v_mul_f32_e32 v120, v112, v112
	v_max_f32_e32 v112, v117, v117
	v_max_f32_e32 v116, v116, v116
	v_max_f32_e32 v112, 0, v112
	v_mul_f32_e32 v117, v113, v113
	v_max_f32_e32 v113, v118, v118
	v_mul_f32_e32 v118, v114, v114
	v_max_f32_e32 v114, v119, v119
	v_max_f32_e32 v115, v115, v115
	v_max_f32_e32 v116, 0, v116
	v_mul_f32_e32 v112, v112, v112
	v_max_f32_e32 v113, 0, v113
	v_max_f32_e32 v114, 0, v114
	v_max_f32_e32 v115, 0, v115
	v_mul_f32_e32 v116, v116, v116
	v_mul_f32_e32 v113, v113, v113
	v_mul_f32_e32 v114, v114, v114
	v_mul_f32_e32 v115, v115, v115
	v_cvt_pk_bf16_f32 v112, v116, v112
	v_max_f32_e32 v104, v104, v104
	v_cvt_pk_bf16_f32 v113, v113, v114
	v_cvt_pk_bf16_f32 v114, v120, v117
	v_cvt_pk_bf16_f32 v115, v118, v115
	global_store_dwordx4 v[138:139], v[112:115], off offset:256
	v_max_f32_e32 v104, 0, v104
	v_max_f32_e32 v105, v105, v105
	v_or_b32_e32 v112, 16, v144
	v_max_f32_e32 v106, v106, v106
	v_ashrrev_i32_e32 v113, 31, v112
	v_mul_f32_e32 v114, v104, v104
	v_max_f32_e32 v104, v109, v109
	v_max_f32_e32 v105, 0, v105
	v_max_f32_e32 v106, 0, v106
	v_lshlrev_b64 v[112:113], 14, v[112:113]
	v_max_f32_e32 v108, v108, v108
	v_max_f32_e32 v104, 0, v104
	v_mul_f32_e32 v109, v105, v105
	v_max_f32_e32 v105, v110, v110
	v_mul_f32_e32 v110, v106, v106
	v_max_f32_e32 v106, v111, v111
	v_max_f32_e32 v107, v107, v107
	v_lshl_add_u64 v[112:113], s[16:17], 0, v[112:113]
	v_max_f32_e32 v108, 0, v108
	v_mul_f32_e32 v104, v104, v104
	v_max_f32_e32 v105, 0, v105
	v_max_f32_e32 v106, 0, v106
	v_max_f32_e32 v107, 0, v107
	v_max_f32_e32 v96, v96, v96
	v_lshl_add_u64 v[112:113], v[112:113], 0, v[148:149]
	v_mul_f32_e32 v108, v108, v108
	v_mul_f32_e32 v105, v105, v105
	v_mul_f32_e32 v106, v106, v106
	v_mul_f32_e32 v107, v107, v107
	v_cvt_pk_bf16_f32 v104, v108, v104
	v_max_f32_e32 v96, 0, v96
	v_max_f32_e32 v97, v97, v97
	v_max_f32_e32 v98, v98, v98
	v_cvt_pk_bf16_f32 v105, v105, v106
	v_cvt_pk_bf16_f32 v106, v114, v109
	v_cvt_pk_bf16_f32 v107, v110, v107
	global_store_dwordx4 v[112:113], v[104:107], off
	v_max_f32_e32 v97, 0, v97
	v_max_f32_e32 v98, 0, v98
	v_mul_f32_e32 v104, v96, v96
	v_max_f32_e32 v96, v101, v101
	v_max_f32_e32 v100, v100, v100
	v_max_f32_e32 v96, 0, v96
	v_mul_f32_e32 v101, v97, v97
	v_max_f32_e32 v97, v102, v102
	v_mul_f32_e32 v102, v98, v98
	v_max_f32_e32 v98, v103, v103
	v_max_f32_e32 v99, v99, v99
	v_max_f32_e32 v100, 0, v100
	v_mul_f32_e32 v96, v96, v96
	v_max_f32_e32 v97, 0, v97
	v_max_f32_e32 v98, 0, v98
	v_max_f32_e32 v99, 0, v99
	v_mul_f32_e32 v100, v100, v100
	v_mul_f32_e32 v97, v97, v97
	v_mul_f32_e32 v98, v98, v98
	v_mul_f32_e32 v99, v99, v99
	v_cvt_pk_bf16_f32 v96, v100, v96
	v_max_f32_e32 v88, v88, v88
	v_cvt_pk_bf16_f32 v97, v97, v98
	v_cvt_pk_bf16_f32 v98, v104, v101
	v_cvt_pk_bf16_f32 v99, v102, v99
	global_store_dwordx4 v[112:113], v[96:99], off offset:256
	v_max_f32_e32 v88, 0, v88
	v_max_f32_e32 v89, v89, v89
	v_or_b32_e32 v96, 32, v144
	v_max_f32_e32 v90, v90, v90
	v_ashrrev_i32_e32 v97, 31, v96
	v_mul_f32_e32 v98, v88, v88
	v_max_f32_e32 v88, v93, v93
	v_max_f32_e32 v89, 0, v89
	v_max_f32_e32 v90, 0, v90
	v_lshlrev_b64 v[96:97], 14, v[96:97]
	v_max_f32_e32 v92, v92, v92
	v_max_f32_e32 v88, 0, v88
	v_mul_f32_e32 v93, v89, v89
	v_max_f32_e32 v89, v94, v94
	v_mul_f32_e32 v94, v90, v90
	v_max_f32_e32 v90, v95, v95
	v_max_f32_e32 v91, v91, v91
	v_lshl_add_u64 v[96:97], s[16:17], 0, v[96:97]
	v_max_f32_e32 v92, 0, v92
	v_mul_f32_e32 v88, v88, v88
	v_max_f32_e32 v89, 0, v89
	v_max_f32_e32 v90, 0, v90
	v_max_f32_e32 v91, 0, v91
	v_max_f32_e32 v80, v80, v80
	v_lshl_add_u64 v[96:97], v[96:97], 0, v[148:149]
	v_mul_f32_e32 v92, v92, v92
	v_mul_f32_e32 v89, v89, v89
	v_mul_f32_e32 v90, v90, v90
	v_mul_f32_e32 v91, v91, v91
	v_cvt_pk_bf16_f32 v88, v92, v88
	v_max_f32_e32 v80, 0, v80
	v_max_f32_e32 v81, v81, v81
	v_max_f32_e32 v82, v82, v82
	v_cvt_pk_bf16_f32 v89, v89, v90
	v_cvt_pk_bf16_f32 v90, v98, v93
	v_cvt_pk_bf16_f32 v91, v94, v91
	global_store_dwordx4 v[96:97], v[88:91], off
	v_max_f32_e32 v81, 0, v81
	v_max_f32_e32 v82, 0, v82
	v_mul_f32_e32 v88, v80, v80
	v_max_f32_e32 v80, v85, v85
	v_max_f32_e32 v84, v84, v84
	v_max_f32_e32 v80, 0, v80
	v_mul_f32_e32 v85, v81, v81
	v_max_f32_e32 v81, v86, v86
	v_mul_f32_e32 v86, v82, v82
	v_max_f32_e32 v82, v87, v87
	v_max_f32_e32 v83, v83, v83
	v_max_f32_e32 v84, 0, v84
	v_mul_f32_e32 v80, v80, v80
	v_max_f32_e32 v81, 0, v81
	v_max_f32_e32 v82, 0, v82
	v_max_f32_e32 v83, 0, v83
	v_mul_f32_e32 v84, v84, v84
	v_mul_f32_e32 v81, v81, v81
	v_mul_f32_e32 v82, v82, v82
	v_mul_f32_e32 v83, v83, v83
	v_cvt_pk_bf16_f32 v80, v84, v80
	v_max_f32_e32 v72, v72, v72
	v_cvt_pk_bf16_f32 v81, v81, v82
	v_cvt_pk_bf16_f32 v82, v88, v85
	v_cvt_pk_bf16_f32 v83, v86, v83
	global_store_dwordx4 v[96:97], v[80:83], off offset:256
	v_max_f32_e32 v72, 0, v72
	v_max_f32_e32 v73, v73, v73
	v_or_b32_e32 v80, 48, v144
	v_max_f32_e32 v74, v74, v74
	v_ashrrev_i32_e32 v81, 31, v80
	v_mul_f32_e32 v82, v72, v72
	v_max_f32_e32 v72, v77, v77
	v_max_f32_e32 v73, 0, v73
	v_max_f32_e32 v74, 0, v74
	v_lshlrev_b64 v[80:81], 14, v[80:81]
	v_max_f32_e32 v76, v76, v76
	v_max_f32_e32 v72, 0, v72
	v_mul_f32_e32 v77, v73, v73
	v_max_f32_e32 v73, v78, v78
	v_mul_f32_e32 v78, v74, v74
	v_max_f32_e32 v74, v79, v79
	v_max_f32_e32 v75, v75, v75
	v_lshl_add_u64 v[80:81], s[16:17], 0, v[80:81]
	v_max_f32_e32 v76, 0, v76
	v_mul_f32_e32 v72, v72, v72
	v_max_f32_e32 v73, 0, v73
	v_max_f32_e32 v74, 0, v74
	v_max_f32_e32 v75, 0, v75
	v_max_f32_e32 v64, v64, v64
	v_max_f32_e32 v65, v65, v65
	v_max_f32_e32 v66, v66, v66
	v_lshl_add_u64 v[80:81], v[80:81], 0, v[148:149]
	v_mul_f32_e32 v76, v76, v76
	v_mul_f32_e32 v73, v73, v73
	v_mul_f32_e32 v74, v74, v74
	v_mul_f32_e32 v75, v75, v75
	v_cvt_pk_bf16_f32 v72, v76, v72
	v_max_f32_e32 v64, 0, v64
	v_max_f32_e32 v65, 0, v65
	v_max_f32_e32 v66, 0, v66
	v_cvt_pk_bf16_f32 v73, v73, v74
	v_cvt_pk_bf16_f32 v74, v82, v77
	v_cvt_pk_bf16_f32 v75, v78, v75
	global_store_dwordx4 v[80:81], v[72:75], off
	v_max_f32_e32 v68, v68, v68
	v_max_f32_e32 v67, v67, v67
	v_mul_f32_e32 v72, v64, v64
	v_max_f32_e32 v64, v69, v69
	v_mul_f32_e32 v69, v65, v65
	v_max_f32_e32 v65, v70, v70
	v_mul_f32_e32 v70, v66, v66
	v_max_f32_e32 v66, v71, v71
	v_max_f32_e32 v64, 0, v64
	v_max_f32_e32 v65, 0, v65
	v_max_f32_e32 v66, 0, v66
	v_max_f32_e32 v68, 0, v68
	v_mul_f32_e32 v64, v64, v64
	v_mul_f32_e32 v65, v65, v65
	v_max_f32_e32 v67, 0, v67
	v_mul_f32_e32 v66, v66, v66
	v_max_f32_e32 v56, v56, v56
	v_mul_f32_e32 v68, v68, v68
	v_mul_f32_e32 v67, v67, v67
	v_cvt_pk_bf16_f32 v64, v68, v64
	v_cvt_pk_bf16_f32 v65, v65, v66
	v_cvt_pk_bf16_f32 v66, v72, v69
	v_max_f32_e32 v56, 0, v56
	v_max_f32_e32 v57, v57, v57
	v_max_f32_e32 v58, v58, v58
	v_cvt_pk_bf16_f32 v67, v70, v67
	global_store_dwordx4 v[80:81], v[64:67], off offset:256
	v_max_f32_e32 v60, v60, v60
	v_max_f32_e32 v57, 0, v57
	v_mul_f32_e32 v66, v56, v56
	v_max_f32_e32 v56, v61, v61
	v_max_f32_e32 v58, 0, v58
	s_mov_b64 s[6:7], 0x200000
	v_max_f32_e32 v60, 0, v60
	v_max_f32_e32 v56, 0, v56
	v_mul_f32_e32 v61, v57, v57
	v_max_f32_e32 v57, v62, v62
	v_mul_f32_e32 v62, v58, v58
	v_max_f32_e32 v58, v63, v63
	v_lshl_add_u64 v[64:65], v[138:139], 0, s[6:7]
	v_mul_f32_e32 v60, v60, v60
	v_mul_f32_e32 v56, v56, v56
	v_max_f32_e32 v57, 0, v57
	v_max_f32_e32 v58, 0, v58
	v_max_f32_e32 v59, v59, v59
	s_mov_b32 s6, 0x200000
	v_mul_f32_e32 v57, v57, v57
	v_max_f32_e32 v59, 0, v59
	v_mul_f32_e32 v58, v58, v58
	v_cvt_pk_bf16_f32 v56, v60, v56
	v_add_co_u32_e32 v60, vcc, s6, v138
	v_max_f32_e32 v48, v48, v48
	v_max_f32_e32 v49, v49, v49
	v_max_f32_e32 v50, v50, v50
	v_mul_f32_e32 v59, v59, v59
	v_cvt_pk_bf16_f32 v57, v57, v58
	v_cvt_pk_bf16_f32 v58, v66, v61
	v_addc_co_u32_e32 v61, vcc, 0, v139, vcc
	v_max_f32_e32 v48, 0, v48
	v_max_f32_e32 v49, 0, v49
	v_max_f32_e32 v50, 0, v50
	v_cvt_pk_bf16_f32 v59, v62, v59
	global_store_dwordx4 v[60:61], v[56:59], off
	v_max_f32_e32 v52, v52, v52
	v_max_f32_e32 v51, v51, v51
	v_mul_f32_e32 v56, v48, v48
	v_max_f32_e32 v48, v53, v53
	v_mul_f32_e32 v53, v49, v49
	v_max_f32_e32 v49, v54, v54
	v_mul_f32_e32 v54, v50, v50
	v_max_f32_e32 v50, v55, v55
	v_max_f32_e32 v48, 0, v48
	v_max_f32_e32 v49, 0, v49
	v_max_f32_e32 v50, 0, v50
	v_max_f32_e32 v52, 0, v52
	v_mul_f32_e32 v48, v48, v48
	v_mul_f32_e32 v49, v49, v49
	v_max_f32_e32 v51, 0, v51
	v_mul_f32_e32 v50, v50, v50
	v_max_f32_e32 v40, v40, v40
	v_mul_f32_e32 v52, v52, v52
	v_mul_f32_e32 v51, v51, v51
	v_cvt_pk_bf16_f32 v48, v52, v48
	v_cvt_pk_bf16_f32 v49, v49, v50
	v_cvt_pk_bf16_f32 v50, v56, v53
	v_max_f32_e32 v40, 0, v40
	v_max_f32_e32 v41, v41, v41
	v_max_f32_e32 v42, v42, v42
	v_cvt_pk_bf16_f32 v51, v54, v51
	global_store_dwordx4 v[64:65], v[48:51], off offset:256
	v_max_f32_e32 v44, v44, v44
	v_max_f32_e32 v41, 0, v41
	v_mul_f32_e32 v50, v40, v40
	v_max_f32_e32 v40, v45, v45
	v_max_f32_e32 v42, 0, v42
	s_mov_b64 s[6:7], 0x240000
	v_max_f32_e32 v44, 0, v44
	v_max_f32_e32 v40, 0, v40
	v_mul_f32_e32 v45, v41, v41
	v_max_f32_e32 v41, v46, v46
	v_mul_f32_e32 v46, v42, v42
	v_max_f32_e32 v42, v47, v47
	v_lshl_add_u64 v[48:49], v[138:139], 0, s[6:7]
	v_mul_f32_e32 v44, v44, v44
	v_mul_f32_e32 v40, v40, v40
	v_max_f32_e32 v41, 0, v41
	v_max_f32_e32 v42, 0, v42
	v_max_f32_e32 v43, v43, v43
	s_mov_b32 s6, 0x240000
	v_mul_f32_e32 v41, v41, v41
	v_max_f32_e32 v43, 0, v43
	v_mul_f32_e32 v42, v42, v42
	v_cvt_pk_bf16_f32 v40, v44, v40
	v_add_co_u32_e32 v44, vcc, s6, v138
	v_max_f32_e32 v32, v32, v32
	v_max_f32_e32 v33, v33, v33
	v_max_f32_e32 v34, v34, v34
	v_mul_f32_e32 v43, v43, v43
	v_cvt_pk_bf16_f32 v41, v41, v42
	v_cvt_pk_bf16_f32 v42, v50, v45
	v_addc_co_u32_e32 v45, vcc, 0, v139, vcc
	v_max_f32_e32 v32, 0, v32
	v_max_f32_e32 v33, 0, v33
	v_max_f32_e32 v34, 0, v34
	v_cvt_pk_bf16_f32 v43, v46, v43
	global_store_dwordx4 v[44:45], v[40:43], off
	v_max_f32_e32 v36, v36, v36
	v_max_f32_e32 v35, v35, v35
	v_mul_f32_e32 v40, v32, v32
	v_max_f32_e32 v32, v37, v37
	v_mul_f32_e32 v37, v33, v33
	v_max_f32_e32 v33, v38, v38
	v_mul_f32_e32 v38, v34, v34
	v_max_f32_e32 v34, v39, v39
	v_max_f32_e32 v32, 0, v32
	v_max_f32_e32 v33, 0, v33
	v_max_f32_e32 v34, 0, v34
	v_max_f32_e32 v36, 0, v36
	v_mul_f32_e32 v32, v32, v32
	v_mul_f32_e32 v33, v33, v33
	v_max_f32_e32 v35, 0, v35
	v_mul_f32_e32 v34, v34, v34
	v_max_f32_e32 v24, v24, v24
	v_mul_f32_e32 v36, v36, v36
	v_mul_f32_e32 v35, v35, v35
	v_cvt_pk_bf16_f32 v32, v36, v32
	v_cvt_pk_bf16_f32 v33, v33, v34
	v_cvt_pk_bf16_f32 v34, v40, v37
	v_max_f32_e32 v24, 0, v24
	v_max_f32_e32 v25, v25, v25
	v_max_f32_e32 v26, v26, v26
	v_cvt_pk_bf16_f32 v35, v38, v35
	global_store_dwordx4 v[48:49], v[32:35], off offset:256
	v_max_f32_e32 v28, v28, v28
	v_max_f32_e32 v25, 0, v25
	v_mul_f32_e32 v34, v24, v24
	v_max_f32_e32 v24, v29, v29
	v_max_f32_e32 v26, 0, v26
	s_mov_b64 s[6:7], 0x280000
	v_max_f32_e32 v28, 0, v28
	v_max_f32_e32 v24, 0, v24
	v_mul_f32_e32 v29, v25, v25
	v_max_f32_e32 v25, v30, v30
	v_mul_f32_e32 v30, v26, v26
	v_max_f32_e32 v26, v31, v31
	v_lshl_add_u64 v[32:33], v[138:139], 0, s[6:7]
	v_mul_f32_e32 v28, v28, v28
	v_mul_f32_e32 v24, v24, v24
	v_max_f32_e32 v25, 0, v25
	v_max_f32_e32 v26, 0, v26
	v_max_f32_e32 v27, v27, v27
	s_mov_b32 s6, 0x280000
	v_mul_f32_e32 v25, v25, v25
	v_max_f32_e32 v27, 0, v27
	v_mul_f32_e32 v26, v26, v26
	v_cvt_pk_bf16_f32 v24, v28, v24
	v_add_co_u32_e32 v28, vcc, s6, v138
	v_max_f32_e32 v16, v16, v16
	v_max_f32_e32 v17, v17, v17
	v_max_f32_e32 v18, v18, v18
	v_mul_f32_e32 v27, v27, v27
	v_cvt_pk_bf16_f32 v25, v25, v26
	v_cvt_pk_bf16_f32 v26, v34, v29
	v_addc_co_u32_e32 v29, vcc, 0, v139, vcc
	v_max_f32_e32 v16, 0, v16
	v_max_f32_e32 v17, 0, v17
	v_max_f32_e32 v18, 0, v18
	v_cvt_pk_bf16_f32 v27, v30, v27
	global_store_dwordx4 v[28:29], v[24:27], off
	v_max_f32_e32 v20, v20, v20
	v_max_f32_e32 v19, v19, v19
	v_mul_f32_e32 v24, v16, v16
	v_max_f32_e32 v16, v21, v21
	v_mul_f32_e32 v21, v17, v17
	v_max_f32_e32 v17, v22, v22
	v_mul_f32_e32 v22, v18, v18
	v_max_f32_e32 v18, v23, v23
	v_max_f32_e32 v16, 0, v16
	v_max_f32_e32 v17, 0, v17
	v_max_f32_e32 v18, 0, v18
	v_max_f32_e32 v20, 0, v20
	v_mul_f32_e32 v16, v16, v16
	v_mul_f32_e32 v17, v17, v17
	v_max_f32_e32 v19, 0, v19
	v_mul_f32_e32 v18, v18, v18
	v_max_f32_e32 v8, v8, v8
	v_mul_f32_e32 v20, v20, v20
	v_mul_f32_e32 v19, v19, v19
	v_cvt_pk_bf16_f32 v16, v20, v16
	v_cvt_pk_bf16_f32 v17, v17, v18
	v_cvt_pk_bf16_f32 v18, v24, v21
	v_max_f32_e32 v8, 0, v8
	v_max_f32_e32 v9, v9, v9
	v_max_f32_e32 v10, v10, v10
	v_cvt_pk_bf16_f32 v19, v22, v19
	global_store_dwordx4 v[32:33], v[16:19], off offset:256
	v_max_f32_e32 v12, v12, v12
	v_max_f32_e32 v9, 0, v9
	v_mul_f32_e32 v18, v8, v8
	v_max_f32_e32 v8, v13, v13
	v_max_f32_e32 v10, 0, v10
	s_mov_b64 s[6:7], 0x2c0000
	v_max_f32_e32 v12, 0, v12
	v_max_f32_e32 v8, 0, v8
	v_mul_f32_e32 v13, v9, v9
	v_max_f32_e32 v9, v14, v14
	v_mul_f32_e32 v14, v10, v10
	v_max_f32_e32 v10, v15, v15
	v_lshl_add_u64 v[16:17], v[138:139], 0, s[6:7]
	v_mul_f32_e32 v12, v12, v12
	v_mul_f32_e32 v8, v8, v8
	v_max_f32_e32 v9, 0, v9
	v_max_f32_e32 v10, 0, v10
	v_max_f32_e32 v11, v11, v11
	s_mov_b32 s6, 0x2c0000
	v_mul_f32_e32 v9, v9, v9
	v_max_f32_e32 v11, 0, v11
	v_mul_f32_e32 v10, v10, v10
	v_cvt_pk_bf16_f32 v8, v12, v8
	v_add_co_u32_e32 v12, vcc, s6, v138
	v_max_f32_e32 v0, v0, v0
	v_max_f32_e32 v1, v1, v1
	v_max_f32_e32 v2, v2, v2
	v_mul_f32_e32 v11, v11, v11
	v_cvt_pk_bf16_f32 v9, v9, v10
	v_cvt_pk_bf16_f32 v10, v18, v13
	v_addc_co_u32_e32 v13, vcc, 0, v139, vcc
	v_max_f32_e32 v0, 0, v0
	v_max_f32_e32 v1, 0, v1
	v_max_f32_e32 v2, 0, v2
	v_cvt_pk_bf16_f32 v11, v14, v11
	global_store_dwordx4 v[12:13], v[8:11], off
	v_max_f32_e32 v3, v3, v3
	v_max_f32_e32 v4, v4, v4
	v_mul_f32_e32 v8, v0, v0
	v_max_f32_e32 v0, v5, v5
	v_mul_f32_e32 v5, v1, v1
	v_max_f32_e32 v1, v6, v6
	v_mul_f32_e32 v6, v2, v2
	v_max_f32_e32 v2, v7, v7
	v_max_f32_e32 v0, 0, v0
	v_max_f32_e32 v1, 0, v1
	v_max_f32_e32 v2, 0, v2
	v_max_f32_e32 v3, 0, v3
	v_max_f32_e32 v4, 0, v4
	v_mul_f32_e32 v0, v0, v0
	v_mul_f32_e32 v1, v1, v1
	v_mul_f32_e32 v2, v2, v2
	v_mul_f32_e32 v3, v3, v3
	s_and_b64 vcc, exec, s[38:39]
	s_mov_b32 s6, s24
	s_mov_b32 s7, s34
	s_mov_b64 s[22:23], s[44:45]
	s_mov_b64 s[20:21], s[42:43]
	v_mul_f32_e32 v4, v4, v4
	v_cvt_pk_bf16_f32 v0, v4, v0
	v_cvt_pk_bf16_f32 v1, v1, v2
	v_cvt_pk_bf16_f32 v2, v8, v5
	v_cvt_pk_bf16_f32 v3, v6, v3
	global_store_dwordx4 v[16:17], v[0:3], off offset:256
	s_cbranch_vccz .LBB0_770
	s_waitcnt vmcnt(0)
	v_readlane_b32 s34, v253, 45
	s_cmpk_gt_u32 s14, 0xff
	v_readlane_b32 s35, v253, 46
	s_cbranch_scc1 .LBB0_777

.LBB0_835:
	s_ashr_i32 s17, s16, 31
	s_lshl_b64 s[6:7], s[16:17], 22
	s_add_u32 s24, s41, s6
	v_cmp_lt_i64_e32 vcc, s[14:15], v[160:161]
	s_addc_u32 s25, s43, s7
	s_ashr_i32 s1, s0, 31
	s_lshl_b64 s[14:15], s[0:1], 22
	s_add_u32 s14, s49, s14
	s_addc_u32 s15, s50, s15
	s_cmp_ge_u32 s2, 0x80
	s_cselect_b32 s100, 0x2000, 0
	s_cmp_eq_u32 s62, 1
	s_cselect_b32 s100, s100, 0
	s_cmp_lg_u32 s98, 0
	s_cselect_b32 s100, s100, 0
	s_add_u32 s24, s24, s100
	s_addc_u32 s25, s25, 0
	s_add_u32 s14, s14, s100
	s_addc_u32 s15, s15, 0
	s_and_b64 s[6:7], vcc, exec
	s_cselect_b32 s6, s25, s21
	s_cselect_b32 s7, s24, s20
	s_and_b64 s[34:35], vcc, exec
	s_cselect_b32 s1, s15, s23
	s_cselect_b32 s17, s14, s22
	s_cmp_lt_u32 s2, 0x80
	s_cselect_b32 s99, 1, 2
	s_cmp_eq_u32 s62, s99
	s_cselect_b32 s99, s99, 0
	s_cmp_lg_u32 s98, 0
	s_cselect_b32 s99, s99, 0
	s_add_u32 s20, s20, 0x200080
	s_addc_u32 s21, s21, 0
	s_add_u32 s63, s22, 0x100
	v_mov_b32_e32 v0, 0
	s_addc_u32 s68, s23, 0
	s_cmp_lg_u32 s99, 0
	s_cselect_b32 s69, 62, -2
	v_mov_b32_e32 v1, v0
	v_mov_b32_e32 v2, v0
	v_mov_b32_e32 v3, v0
	v_mov_b32_e32 v4, v0
	v_mov_b32_e32 v5, v0
	v_mov_b32_e32 v6, v0
	v_mov_b32_e32 v7, v0
	v_mov_b32_e32 v12, v0
	v_mov_b32_e32 v13, v0
	v_mov_b32_e32 v14, v0
	v_mov_b32_e32 v15, v0
	v_mov_b32_e32 v20, v0
	v_mov_b32_e32 v21, v0
	v_mov_b32_e32 v22, v0
	v_mov_b32_e32 v23, v0
	v_mov_b32_e32 v28, v0
	v_mov_b32_e32 v29, v0
	v_mov_b32_e32 v30, v0
	v_mov_b32_e32 v31, v0
	v_mov_b32_e32 v36, v0
	v_mov_b32_e32 v37, v0
	v_mov_b32_e32 v38, v0
	v_mov_b32_e32 v39, v0
	v_mov_b32_e32 v44, v0
	v_mov_b32_e32 v45, v0
	v_mov_b32_e32 v46, v0
	v_mov_b32_e32 v47, v0
	v_mov_b32_e32 v52, v0
	v_mov_b32_e32 v53, v0
	v_mov_b32_e32 v54, v0
	v_mov_b32_e32 v55, v0
	v_mov_b32_e32 v8, v0
	v_mov_b32_e32 v9, v0
	v_mov_b32_e32 v10, v0
	v_mov_b32_e32 v11, v0
	v_mov_b32_e32 v16, v0
	v_mov_b32_e32 v17, v0
	v_mov_b32_e32 v18, v0
	v_mov_b32_e32 v19, v0
	v_mov_b32_e32 v24, v0
	v_mov_b32_e32 v25, v0
	v_mov_b32_e32 v26, v0
	v_mov_b32_e32 v27, v0
	v_mov_b32_e32 v32, v0
	v_mov_b32_e32 v33, v0
	v_mov_b32_e32 v34, v0
	v_mov_b32_e32 v35, v0
	v_mov_b32_e32 v40, v0
	v_mov_b32_e32 v41, v0
	v_mov_b32_e32 v42, v0
	v_mov_b32_e32 v43, v0
	v_mov_b32_e32 v48, v0
	v_mov_b32_e32 v49, v0
	v_mov_b32_e32 v50, v0
	v_mov_b32_e32 v51, v0
	v_mov_b32_e32 v56, v0
	v_mov_b32_e32 v57, v0
	v_mov_b32_e32 v58, v0
	v_mov_b32_e32 v59, v0
	v_mov_b32_e32 v60, v0
	v_mov_b32_e32 v61, v0
	v_mov_b32_e32 v62, v0
	v_mov_b32_e32 v63, v0
	v_mov_b32_e32 v64, v0
	v_mov_b32_e32 v65, v0
	v_mov_b32_e32 v66, v0
	v_mov_b32_e32 v67, v0
	v_mov_b32_e32 v68, v0
	v_mov_b32_e32 v69, v0
	v_mov_b32_e32 v70, v0
	v_mov_b32_e32 v71, v0
	v_mov_b32_e32 v76, v0
	v_mov_b32_e32 v77, v0
	v_mov_b32_e32 v78, v0
	v_mov_b32_e32 v79, v0
	v_mov_b32_e32 v84, v0
	v_mov_b32_e32 v85, v0
	v_mov_b32_e32 v86, v0
	v_mov_b32_e32 v87, v0
	v_mov_b32_e32 v92, v0
	v_mov_b32_e32 v93, v0
	v_mov_b32_e32 v94, v0
	v_mov_b32_e32 v95, v0
	v_mov_b32_e32 v100, v0
	v_mov_b32_e32 v101, v0
	v_mov_b32_e32 v102, v0
	v_mov_b32_e32 v103, v0
	v_mov_b32_e32 v108, v0
	v_mov_b32_e32 v109, v0
	v_mov_b32_e32 v110, v0
	v_mov_b32_e32 v111, v0
	v_mov_b32_e32 v116, v0
	v_mov_b32_e32 v117, v0
	v_mov_b32_e32 v118, v0
	v_mov_b32_e32 v119, v0
	v_mov_b32_e32 v72, v0
	v_mov_b32_e32 v73, v0
	v_mov_b32_e32 v74, v0
	v_mov_b32_e32 v75, v0
	v_mov_b32_e32 v80, v0
	v_mov_b32_e32 v81, v0
	v_mov_b32_e32 v82, v0
	v_mov_b32_e32 v83, v0
	v_mov_b32_e32 v88, v0
	v_mov_b32_e32 v89, v0
	v_mov_b32_e32 v90, v0
	v_mov_b32_e32 v91, v0
	v_mov_b32_e32 v96, v0
	v_mov_b32_e32 v97, v0
	v_mov_b32_e32 v98, v0
	v_mov_b32_e32 v99, v0
	v_mov_b32_e32 v104, v0
	v_mov_b32_e32 v105, v0
	v_mov_b32_e32 v106, v0
	v_mov_b32_e32 v107, v0
	v_mov_b32_e32 v112, v0
	v_mov_b32_e32 v113, v0
	v_mov_b32_e32 v114, v0
	v_mov_b32_e32 v115, v0
	v_mov_b32_e32 v128, v0
	v_mov_b32_e32 v129, v0
	v_mov_b32_e32 v130, v0
	v_mov_b32_e32 v131, v0
	v_mov_b32_e32 v140, v0
	v_mov_b32_e32 v141, v0
	v_mov_b32_e32 v142, v0
	v_mov_b32_e32 v143, v0
	s_cmpk_lt_u32 s42, 0x100
	s_cbranch_scc1 .Lal_e1_q
	s_cmp_lt_u32 s62, 2
	s_cbranch_scc1 .Lal_e1_q
	s_barrier
.Lal_e1_q:
	v_writelane_b32 v246, s98, 0
	v_writelane_b32 v246, s99, 1
	v_add_u32_e32 v248, 0x10000, v183
	v_add_u32_e32 v249, 0x14000, v183
	v_add_u32_e32 v250, 0x18000, v183
	v_add_u32_e32 v251, 0x1c000, v183
	s_add_u32 s22, s20, 0xffe00080
	s_addc_u32 s23, s21, -1
	s_add_i32 s78, 0, 0x10000
	s_cmpk_eq_i32 s69, 0x7c
	s_cselect_b32 s35, s6, s23
	s_cselect_b32 s34, s7, s22
	s_cselect_b32 s23, s1, s68
	s_cselect_b32 s22, s17, s63
	s_add_i32 m0, s52, 0xc000
.LBB0_836:
	ds_read_b128 v[120:123], v248
	ds_read_b128 v[124:127], v248 offset:1024
	ds_read_b128 v[132:135], v248 offset:2048
	ds_read_b128 v[136:139], v248 offset:3072
	ds_read_b128 v[186:189], v185
	ds_read_b128 v[190:193], v185 offset:1024
	ds_read_b128 v[206:209], v185 offset:2048
	ds_read_b128 v[210:213], v185 offset:3072
	ds_read_b128 v[214:217], v185 offset:4096
	ds_read_b128 v[218:221], v185 offset:5120
	ds_read_b128 v[222:225], v185 offset:6144
	ds_read_b128 v[226:229], v185 offset:7168
	global_load_lds_dwordx4 v176, s[20:21]
	s_add_i32 m0, s52, 0xe000
	s_nop 0
	global_load_lds_dwordx4 v178, s[20:21]
	s_waitcnt lgkmcnt(8)
	s_barrier
	s_waitcnt lgkmcnt(0)
	v_mfma_f32_16x16x32_bf16 v[140:143], v[120:123], v[186:189], v[140:143]
	v_mfma_f32_16x16x32_bf16 v[128:131], v[132:135], v[186:189], v[128:131]
	v_mfma_f32_16x16x32_bf16 v[112:115], v[120:123], v[206:209], v[112:115]
	v_mfma_f32_16x16x32_bf16 v[104:107], v[132:135], v[206:209], v[104:107]
	v_mfma_f32_16x16x32_bf16 v[96:99], v[120:123], v[214:217], v[96:99]
	v_mfma_f32_16x16x32_bf16 v[88:91], v[132:135], v[214:217], v[88:91]
	v_mfma_f32_16x16x32_bf16 v[80:83], v[120:123], v[222:225], v[80:83]
	v_mfma_f32_16x16x32_bf16 v[72:75], v[132:135], v[222:225], v[72:75]
	v_mfma_f32_16x16x32_bf16 v[140:143], v[124:127], v[190:193], v[140:143]
	v_mfma_f32_16x16x32_bf16 v[128:131], v[136:139], v[190:193], v[128:131]
	v_mfma_f32_16x16x32_bf16 v[112:115], v[124:127], v[210:213], v[112:115]
	v_mfma_f32_16x16x32_bf16 v[104:107], v[136:139], v[210:213], v[104:107]
	v_mfma_f32_16x16x32_bf16 v[96:99], v[124:127], v[218:221], v[96:99]
	v_mfma_f32_16x16x32_bf16 v[88:91], v[136:139], v[218:221], v[88:91]
	v_mfma_f32_16x16x32_bf16 v[80:83], v[124:127], v[226:229], v[80:83]
	v_mfma_f32_16x16x32_bf16 v[72:75], v[136:139], v[226:229], v[72:75]
	s_barrier
	s_add_i32 s80, 0, 0x14000
	s_add_i32 s78, s78, s51
	ds_read_b128 v[230:233], v249
	ds_read_b128 v[234:237], v249 offset:1024
	ds_read_b128 v[238:241], v249 offset:2048
	ds_read_b128 v[242:245], v249 offset:3072
	s_mov_b32 m0, s78
	s_nop 0
	global_load_lds_dwordx4 v152, s[22:23]
	s_add_i32 m0, s78, 0x2000
	s_nop 0
	global_load_lds_dwordx4 v144, s[22:23]
	s_barrier
	s_waitcnt lgkmcnt(0)
	v_mfma_f32_16x16x32_bf16 v[116:119], v[230:233], v[186:189], v[116:119]
	v_mfma_f32_16x16x32_bf16 v[108:111], v[238:241], v[186:189], v[108:111]
	v_mfma_f32_16x16x32_bf16 v[100:103], v[230:233], v[206:209], v[100:103]
	v_mfma_f32_16x16x32_bf16 v[92:95], v[238:241], v[206:209], v[92:95]
	v_mfma_f32_16x16x32_bf16 v[84:87], v[230:233], v[214:217], v[84:87]
	v_mfma_f32_16x16x32_bf16 v[76:79], v[238:241], v[214:217], v[76:79]
	v_mfma_f32_16x16x32_bf16 v[68:71], v[230:233], v[222:225], v[68:71]
	v_mfma_f32_16x16x32_bf16 v[64:67], v[238:241], v[222:225], v[64:67]
	v_mfma_f32_16x16x32_bf16 v[116:119], v[234:237], v[190:193], v[116:119]
	v_mfma_f32_16x16x32_bf16 v[108:111], v[242:245], v[190:193], v[108:111]
	v_mfma_f32_16x16x32_bf16 v[100:103], v[234:237], v[210:213], v[100:103]
	v_mfma_f32_16x16x32_bf16 v[92:95], v[242:245], v[210:213], v[92:95]
	v_mfma_f32_16x16x32_bf16 v[84:87], v[234:237], v[218:221], v[84:87]
	v_mfma_f32_16x16x32_bf16 v[76:79], v[242:245], v[218:221], v[76:79]
	v_mfma_f32_16x16x32_bf16 v[68:71], v[234:237], v[226:229], v[68:71]
	v_mfma_f32_16x16x32_bf16 v[64:67], v[242:245], v[226:229], v[64:67]
	s_barrier
	s_mov_b32 m0, s52
	s_add_u32 s98, s34, 0x80
	s_addc_u32 s99, s35, 0
	ds_read_b128 v[186:189], v185 offset:16384
	ds_read_b128 v[190:193], v185 offset:17408
	ds_read_b128 v[206:209], v185 offset:18432
	ds_read_b128 v[210:213], v185 offset:19456
	ds_read_b128 v[214:217], v185 offset:20480
	ds_read_b128 v[218:221], v185 offset:21504
	ds_read_b128 v[222:225], v185 offset:22528
	ds_read_b128 v[226:229], v185 offset:23552
	global_load_lds_dwordx4 v148, s[34:35]
	s_mov_b32 m0, s53
	s_nop 0
	global_load_lds_dwordx4 v146, s[34:35]
	s_barrier
	s_waitcnt lgkmcnt(0)
	v_mfma_f32_16x16x32_bf16 v[60:63], v[120:123], v[186:189], v[60:63]
	v_mfma_f32_16x16x32_bf16 v[56:59], v[132:135], v[186:189], v[56:59]
	v_mfma_f32_16x16x32_bf16 v[48:51], v[120:123], v[206:209], v[48:51]
	v_mfma_f32_16x16x32_bf16 v[40:43], v[132:135], v[206:209], v[40:43]
	v_mfma_f32_16x16x32_bf16 v[32:35], v[120:123], v[214:217], v[32:35]
	v_mfma_f32_16x16x32_bf16 v[24:27], v[132:135], v[214:217], v[24:27]
	v_mfma_f32_16x16x32_bf16 v[16:19], v[120:123], v[222:225], v[16:19]
	v_mfma_f32_16x16x32_bf16 v[8:11], v[132:135], v[222:225], v[8:11]
	v_mfma_f32_16x16x32_bf16 v[60:63], v[124:127], v[190:193], v[60:63]
	v_mfma_f32_16x16x32_bf16 v[56:59], v[136:139], v[190:193], v[56:59]
	v_mfma_f32_16x16x32_bf16 v[48:51], v[124:127], v[210:213], v[48:51]
	v_mfma_f32_16x16x32_bf16 v[40:43], v[136:139], v[210:213], v[40:43]
	v_mfma_f32_16x16x32_bf16 v[32:35], v[124:127], v[218:221], v[32:35]
	v_mfma_f32_16x16x32_bf16 v[24:27], v[136:139], v[218:221], v[24:27]
	v_mfma_f32_16x16x32_bf16 v[16:19], v[124:127], v[226:229], v[16:19]
	v_mfma_f32_16x16x32_bf16 v[8:11], v[136:139], v[226:229], v[8:11]
	s_barrier
	s_add_u32 s78, s22, 0x200000
	s_addc_u32 s79, s23, 0
	s_add_i32 s80, s80, s51
	s_mov_b32 m0, s80
	s_nop 0
	global_load_lds_dwordx4 v152, s[78:79]
	s_add_i32 m0, s80, 0x2000
	s_nop 0
	global_load_lds_dwordx4 v144, s[78:79]
	s_add_i32 s78, 0, 0x18000
	s_add_u32 s34, s34, 0x200000
	s_addc_u32 s35, s35, 0
	s_mov_b32 m0, s54
	s_waitcnt vmcnt(6)
	s_barrier
	v_mfma_f32_16x16x32_bf16 v[52:55], v[230:233], v[186:189], v[52:55]
	v_mfma_f32_16x16x32_bf16 v[44:47], v[238:241], v[186:189], v[44:47]
	v_mfma_f32_16x16x32_bf16 v[36:39], v[230:233], v[206:209], v[36:39]
	v_mfma_f32_16x16x32_bf16 v[28:31], v[238:241], v[206:209], v[28:31]
	v_mfma_f32_16x16x32_bf16 v[20:23], v[230:233], v[214:217], v[20:23]
	v_mfma_f32_16x16x32_bf16 v[12:15], v[238:241], v[214:217], v[12:15]
	v_mfma_f32_16x16x32_bf16 v[4:7], v[230:233], v[222:225], v[4:7]
	v_mfma_f32_16x16x32_bf16 v[0:3], v[238:241], v[222:225], v[0:3]
	v_mfma_f32_16x16x32_bf16 v[52:55], v[234:237], v[190:193], v[52:55]
	v_mfma_f32_16x16x32_bf16 v[44:47], v[242:245], v[190:193], v[44:47]
	v_mfma_f32_16x16x32_bf16 v[36:39], v[234:237], v[210:213], v[36:39]
	v_mfma_f32_16x16x32_bf16 v[28:31], v[242:245], v[210:213], v[28:31]
	v_mfma_f32_16x16x32_bf16 v[20:23], v[234:237], v[218:221], v[20:23]
	v_mfma_f32_16x16x32_bf16 v[12:15], v[242:245], v[218:221], v[12:15]
	v_mfma_f32_16x16x32_bf16 v[4:7], v[234:237], v[226:229], v[4:7]
	v_mfma_f32_16x16x32_bf16 v[0:3], v[242:245], v[226:229], v[0:3]
	s_barrier
	ds_read_b128 v[120:123], v250
	ds_read_b128 v[124:127], v250 offset:1024
	ds_read_b128 v[132:135], v250 offset:2048
	ds_read_b128 v[136:139], v250 offset:3072
	ds_read_b128 v[186:189], v185 offset:32768
	ds_read_b128 v[190:193], v185 offset:33792
	ds_read_b128 v[206:209], v185 offset:34816
	ds_read_b128 v[210:213], v185 offset:35840
	ds_read_b128 v[214:217], v185 offset:36864
	ds_read_b128 v[218:221], v185 offset:37888
	ds_read_b128 v[222:225], v185 offset:38912
	ds_read_b128 v[226:229], v185 offset:39936
	global_load_lds_dwordx4 v148, s[34:35]
	s_mov_b32 m0, s55
	s_nop 0
	global_load_lds_dwordx4 v146, s[34:35]
	s_waitcnt lgkmcnt(8)
	s_barrier
	s_waitcnt lgkmcnt(0)
	v_mfma_f32_16x16x32_bf16 v[140:143], v[120:123], v[186:189], v[140:143]
	v_mfma_f32_16x16x32_bf16 v[128:131], v[132:135], v[186:189], v[128:131]
	v_mfma_f32_16x16x32_bf16 v[112:115], v[120:123], v[206:209], v[112:115]
	v_mfma_f32_16x16x32_bf16 v[104:107], v[132:135], v[206:209], v[104:107]
	v_mfma_f32_16x16x32_bf16 v[96:99], v[120:123], v[214:217], v[96:99]
	v_mfma_f32_16x16x32_bf16 v[88:91], v[132:135], v[214:217], v[88:91]
	v_mfma_f32_16x16x32_bf16 v[80:83], v[120:123], v[222:225], v[80:83]
	v_mfma_f32_16x16x32_bf16 v[72:75], v[132:135], v[222:225], v[72:75]
	v_mfma_f32_16x16x32_bf16 v[140:143], v[124:127], v[190:193], v[140:143]
	v_mfma_f32_16x16x32_bf16 v[128:131], v[136:139], v[190:193], v[128:131]
	v_mfma_f32_16x16x32_bf16 v[112:115], v[124:127], v[210:213], v[112:115]
	v_mfma_f32_16x16x32_bf16 v[104:107], v[136:139], v[210:213], v[104:107]
	v_mfma_f32_16x16x32_bf16 v[96:99], v[124:127], v[218:221], v[96:99]
	v_mfma_f32_16x16x32_bf16 v[88:91], v[136:139], v[218:221], v[88:91]
	v_mfma_f32_16x16x32_bf16 v[80:83], v[124:127], v[226:229], v[80:83]
	v_mfma_f32_16x16x32_bf16 v[72:75], v[136:139], v[226:229], v[72:75]
	s_barrier
	s_add_i32 s34, 0, 0x1c000
	s_add_i32 s35, s78, s51
	s_add_u32 s100, s22, 0x80
	s_addc_u32 s101, s23, 0
	s_mov_b32 m0, s35
	ds_read_b128 v[230:233], v251
	ds_read_b128 v[234:237], v251 offset:1024
	ds_read_b128 v[238:241], v251 offset:2048
	ds_read_b128 v[242:245], v251 offset:3072
	global_load_lds_dwordx4 v152, s[100:101]
	s_add_i32 m0, s35, 0x2000
	s_nop 0
	global_load_lds_dwordx4 v144, s[100:101]
	s_barrier
	s_waitcnt lgkmcnt(0)
	v_mfma_f32_16x16x32_bf16 v[116:119], v[230:233], v[186:189], v[116:119]
	v_mfma_f32_16x16x32_bf16 v[108:111], v[238:241], v[186:189], v[108:111]
	v_mfma_f32_16x16x32_bf16 v[100:103], v[230:233], v[206:209], v[100:103]
	v_mfma_f32_16x16x32_bf16 v[92:95], v[238:241], v[206:209], v[92:95]
	v_mfma_f32_16x16x32_bf16 v[84:87], v[230:233], v[214:217], v[84:87]
	v_mfma_f32_16x16x32_bf16 v[76:79], v[238:241], v[214:217], v[76:79]
	v_mfma_f32_16x16x32_bf16 v[68:71], v[230:233], v[222:225], v[68:71]
	v_mfma_f32_16x16x32_bf16 v[64:67], v[238:241], v[222:225], v[64:67]
	v_mfma_f32_16x16x32_bf16 v[116:119], v[234:237], v[190:193], v[116:119]
	v_mfma_f32_16x16x32_bf16 v[108:111], v[242:245], v[190:193], v[108:111]
	v_mfma_f32_16x16x32_bf16 v[100:103], v[234:237], v[210:213], v[100:103]
	v_mfma_f32_16x16x32_bf16 v[92:95], v[242:245], v[210:213], v[92:95]
	v_mfma_f32_16x16x32_bf16 v[84:87], v[234:237], v[218:221], v[84:87]
	v_mfma_f32_16x16x32_bf16 v[76:79], v[242:245], v[218:221], v[76:79]
	v_mfma_f32_16x16x32_bf16 v[68:71], v[234:237], v[226:229], v[68:71]
	v_mfma_f32_16x16x32_bf16 v[64:67], v[242:245], v[226:229], v[64:67]
	s_barrier
	s_mov_b32 m0, s60
	ds_read_b128 v[186:189], v185 offset:49152
	ds_read_b128 v[190:193], v185 offset:50176
	ds_read_b128 v[206:209], v185 offset:51200
	ds_read_b128 v[210:213], v185 offset:52224
	ds_read_b128 v[214:217], v185 offset:53248
	ds_read_b128 v[218:221], v185 offset:54272
	ds_read_b128 v[222:225], v185 offset:55296
	ds_read_b128 v[226:229], v185 offset:56320
	global_load_lds_dwordx4 v148, s[98:99]
	s_mov_b32 m0, s61
	s_nop 0
	global_load_lds_dwordx4 v146, s[98:99]
	s_barrier
	s_waitcnt lgkmcnt(0)
	v_mfma_f32_16x16x32_bf16 v[60:63], v[120:123], v[186:189], v[60:63]
	v_mfma_f32_16x16x32_bf16 v[56:59], v[132:135], v[186:189], v[56:59]
	v_mfma_f32_16x16x32_bf16 v[48:51], v[120:123], v[206:209], v[48:51]
	v_mfma_f32_16x16x32_bf16 v[40:43], v[132:135], v[206:209], v[40:43]
	v_mfma_f32_16x16x32_bf16 v[32:35], v[120:123], v[214:217], v[32:35]
	v_mfma_f32_16x16x32_bf16 v[24:27], v[132:135], v[214:217], v[24:27]
	v_mfma_f32_16x16x32_bf16 v[16:19], v[120:123], v[222:225], v[16:19]
	v_mfma_f32_16x16x32_bf16 v[8:11], v[132:135], v[222:225], v[8:11]
	v_mfma_f32_16x16x32_bf16 v[60:63], v[124:127], v[190:193], v[60:63]
	v_mfma_f32_16x16x32_bf16 v[56:59], v[136:139], v[190:193], v[56:59]
	v_mfma_f32_16x16x32_bf16 v[48:51], v[124:127], v[210:213], v[48:51]
	v_mfma_f32_16x16x32_bf16 v[40:43], v[136:139], v[210:213], v[40:43]
	v_mfma_f32_16x16x32_bf16 v[32:35], v[124:127], v[218:221], v[32:35]
	v_mfma_f32_16x16x32_bf16 v[24:27], v[136:139], v[218:221], v[24:27]
	v_mfma_f32_16x16x32_bf16 v[16:19], v[124:127], v[226:229], v[16:19]
	v_mfma_f32_16x16x32_bf16 v[8:11], v[136:139], v[226:229], v[8:11]
	s_barrier
	s_add_u32 s22, s22, 0x200080
	s_addc_u32 s23, s23, 0
	s_add_i32 s34, s34, s51
	s_mov_b32 m0, s34
	s_nop 0
	global_load_lds_dwordx4 v152, s[22:23]
	s_add_i32 m0, s34, 0x2000
	s_nop 0
	global_load_lds_dwordx4 v144, s[22:23]
	s_add_i32 s69, s69, 2
	s_add_u32 s20, s20, 0x100
	s_addc_u32 s21, s21, 0
	s_add_u32 s63, s63, 0x100
	s_addc_u32 s68, s68, 0
	s_add_u32 s22, s20, 0xffe00080
	s_addc_u32 s23, s21, -1
	s_add_i32 s78, 0, 0x10000
	s_cmpk_eq_i32 s69, 0x7c
	s_cselect_b32 s35, s6, s23
	s_cselect_b32 s34, s7, s22
	s_cselect_b32 s23, s1, s68
	s_cselect_b32 s22, s17, s63
	s_add_i32 m0, s52, 0xc000
	s_cmpk_gt_u32 s69, 0x7d
	s_waitcnt vmcnt(6)
	s_barrier
	v_mfma_f32_16x16x32_bf16 v[52:55], v[230:233], v[186:189], v[52:55]
	v_mfma_f32_16x16x32_bf16 v[44:47], v[238:241], v[186:189], v[44:47]
	v_mfma_f32_16x16x32_bf16 v[36:39], v[230:233], v[206:209], v[36:39]
	v_mfma_f32_16x16x32_bf16 v[28:31], v[238:241], v[206:209], v[28:31]
	v_mfma_f32_16x16x32_bf16 v[20:23], v[230:233], v[214:217], v[20:23]
	v_mfma_f32_16x16x32_bf16 v[12:15], v[238:241], v[214:217], v[12:15]
	v_mfma_f32_16x16x32_bf16 v[4:7], v[230:233], v[222:225], v[4:7]
	v_mfma_f32_16x16x32_bf16 v[0:3], v[238:241], v[222:225], v[0:3]
	v_mfma_f32_16x16x32_bf16 v[52:55], v[234:237], v[190:193], v[52:55]
	v_mfma_f32_16x16x32_bf16 v[44:47], v[242:245], v[190:193], v[44:47]
	v_mfma_f32_16x16x32_bf16 v[36:39], v[234:237], v[210:213], v[36:39]
	v_mfma_f32_16x16x32_bf16 v[28:31], v[242:245], v[210:213], v[28:31]
	v_mfma_f32_16x16x32_bf16 v[20:23], v[234:237], v[218:221], v[20:23]
	v_mfma_f32_16x16x32_bf16 v[12:15], v[242:245], v[218:221], v[12:15]
	v_mfma_f32_16x16x32_bf16 v[4:7], v[234:237], v[226:229], v[4:7]
	v_mfma_f32_16x16x32_bf16 v[0:3], v[242:245], v[226:229], v[0:3]
	s_barrier
	s_cbranch_scc0 .LBB0_836
	s_cmpk_gt_u32 s42, 0xff
	s_cbranch_scc1 .Lal_e0_q
	s_barrier
.Lal_e0_q:
	v_readlane_b32 s98, v246, 0
	v_readlane_b32 s99, v246, 1
	s_cmp_eq_u32 s99, 0
	s_cbranch_scc1 .Lm2_epi
	s_and_b32 s100, s2, 0x7f
	s_lshl_b32 s100, s100, 18
	s_add_u32 s100, s100, 0x29800000
	s_add_u32 s100, s46, s100
	s_addc_u32 s101, s47, 0
	v_lshlrev_b32_e32 v186, 4, v182
	s_cmp_eq_u32 s99, 1
	s_cbranch_scc1 .Lm2_put_partial
	s_and_b32 s6, s2, 0x7f
	s_lshl_b32 s6, s6, 6
	s_add_u32 s6, s6, 0x2970a000
	s_add_u32 s6, s46, s6
	s_addc_u32 s7, s47, 0
	v_mov_b32_e32 v187, 0
	s_mov_b32 s99, 0

.Lm2_epi_tail:
	s_mov_b32 s4, s0
	s_mov_b32 s5, s16
	s_and_b64 vcc, exec, s[38:39]
	s_mov_b64 s[22:23], s[14:15]
	s_mov_b64 s[20:21], s[24:25]
	s_cbranch_vccz .LBB0_833
	s_waitcnt vmcnt(0)
	s_cmpk_gt_u32 s42, 0xff
	s_cbranch_scc1 .LBB0_840
.LBB0_840:
	v_readlane_b32 s34, v253, 45
	v_readlane_b32 s35, v253, 46
	s_barrier
